# v4 + write-through (sc1) stores for the MLP-up GEMM output (268 MB streamed to the down GEMM), cache policy only
# baseline (speedup 1.0000x reference)
; #define PG8_STAGE(bufoff, gbase, voff) do { _Pragma("unroll") for (int _i = 0; _i < 2; ++_i) \
;         __builtin_amdgcn_global_load_lds((const unsigned*)((const char*)(gbase) + (voff)[_i]), (LAS unsigned*)(lds + (bufoff) + ldsw + _i * 8192), 16, 0, 0); } while (0)
; #define PG8_LDA(dst, b, h) do { _Pragma("unroll") for (int m = 0; m < 4; ++m) _Pragma("unroll") for (int k = 0; k < 2; ++k) dst[m][k] = *(const LAS bf16x8*)(lds + PG8_SA(b, h) + aoff + m * 2048 + k * 1024); } while (0)
; #define PG8_LDB(dst, b, h) do { _Pragma("unroll") for (int n = 0; n < 2; ++n) _Pragma("unroll") for (int k = 0; k < 2; ++k) dst[n][k] = *(const LAS bf16x8*)(lds + PG8_SB(b, h) + boff + n * 2048 + k * 1024); } while (0)
; #define PG8_MMA(ai, bj, At, Bt) do { __builtin_amdgcn_s_setprio(1); _Pragma("unroll") for (int m = 0; m < 4; ++m) _Pragma("unroll") for (int n = 0; n < 2; ++n) _Pragma("unroll") for (int k = 0; k < 2; ++k) \
;         acc[ai][bj][m][n] = __builtin_amdgcn_mfma_f32_16x16x32_bf16(Bt[n][k], At[m][k], acc[ai][bj][m][n], 0, 0, 0); __builtin_amdgcn_s_setprio(0); } while (0)
; #define PG8_WAIT_V(n) asm volatile("s_waitcnt vmcnt(" #n ")" ::: "memory")
; template <class Epi>
; __device__ __forceinline__ void gemm_phase(LAS unsigned char* lds, const Gemm g, const StaticOrder& S, const Epi& E, int wv) {
;     ...
;             const bool last = (t == nt - 2);
;             const char* a1 = cA + (ptrdiff_t)(t + 1) * kstep;
;             const char* a2 = last ? nA : cA + (ptrdiff_t)(t + 2) * kstep; const char* b2 = last ? nB : cB + (ptrdiff_t)(t + 2) * kstep;
;             const char* a3 = a2 + kstep; const char* b3 = b2 + kstep;
;             PG8_LDB(B0, 0, 0); PG8_SCHED; PG8_LDA(At, 0, 0); PG8_STAGE(PG8_SA(1, 1), a1 + hstepA, voffA);
;             PG8_WAIT_L(8); PG8_BAR; PG8_WAIT_L(0); PG8_MMA(0, 0, At, B0); PG8_BAR; PG8_SCHED;
;             PG8_LDB(B1, 0, 1); PG8_STAGE(PG8_SB(0, 0), b2, voffB);
;             PG8_BAR; PG8_WAIT_L(0); PG8_MMA(0, 1, At, B1); PG8_BAR;
;             PG8_LDA(At, 0, 1); PG8_STAGE(PG8_SA(0, 0), a2, voffA);
;             PG8_BAR; PG8_WAIT_L(0); PG8_MMA(1, 0, At, B0); PG8_BAR; PG8_SCHED;
;             PG8_STAGE(PG8_SB(0, 1), b2 + hstepB, voffB);
;             PG8_WAIT_V(6); PG8_BAR; PG8_MMA(1, 1, At, B1); PG8_BAR;
;             PG8_LDB(B0, 1, 0); PG8_SCHED; PG8_LDA(At, 1, 0); PG8_STAGE(PG8_SA(0, 1), a2 + hstepA, voffA);
.LBB0_530:
	s_add_u32 s44, s66, 0xfff80080
	s_addc_u32 s45, s67, -1
	s_cmp_eq_u32 s43, 28
	s_cselect_b32 s71, s35, s45
	s_cselect_b32 s70, s38, s44
	s_cselect_b32 s69, s39, s42
	s_cselect_b32 s68, s40, s41
	s_add_i32 m0, s10, 0xc000
	ds_read_b128 v[170:173], v154
	ds_read_b128 v[174:177], v154 offset:1024
	ds_read_b128 v[178:181], v154 offset:2048
	ds_read_b128 v[182:185], v154 offset:3072
	ds_read_b128 v[186:189], v154 offset:4096
	ds_read_b128 v[190:193], v154 offset:5120
	ds_read_b128 v[194:197], v154 offset:6144
	ds_read_b128 v[198:201], v154 offset:7168
	global_load_lds_dwordx4 v138, s[66:67]
	s_add_i32 m0, s10, 0xe000
	s_nop 0
	global_load_lds_dwordx4 v136, s[66:67]
	s_waitcnt lgkmcnt(8)
	s_barrier
	s_waitcnt lgkmcnt(0)
	s_setprio 1
	s_waitcnt lgkmcnt(0)
	v_mfma_f32_16x16x32_bf16 v[124:127], v[144:147], v[170:173], v[124:127]
	v_mfma_f32_16x16x32_bf16 v[120:123], v[162:165], v[170:173], v[120:123]
	v_mfma_f32_16x16x32_bf16 v[116:119], v[144:147], v[178:181], v[116:119]
	v_mfma_f32_16x16x32_bf16 v[112:115], v[162:165], v[178:181], v[112:115]
	v_mfma_f32_16x16x32_bf16 v[92:95], v[144:147], v[186:189], v[92:95]
	v_mfma_f32_16x16x32_bf16 v[88:91], v[162:165], v[186:189], v[88:91]
	v_mfma_f32_16x16x32_bf16 v[76:79], v[144:147], v[194:197], v[76:79]
	v_mfma_f32_16x16x32_bf16 v[72:75], v[162:165], v[194:197], v[72:75]
	v_mfma_f32_16x16x32_bf16 v[124:127], v[158:161], v[174:177], v[124:127]
	v_mfma_f32_16x16x32_bf16 v[120:123], v[166:169], v[174:177], v[120:123]
	v_mfma_f32_16x16x32_bf16 v[116:119], v[158:161], v[182:185], v[116:119]
	v_mfma_f32_16x16x32_bf16 v[112:115], v[166:169], v[182:185], v[112:115]
	v_mfma_f32_16x16x32_bf16 v[92:95], v[158:161], v[190:193], v[92:95]
	v_mfma_f32_16x16x32_bf16 v[88:91], v[166:169], v[190:193], v[88:91]
	v_mfma_f32_16x16x32_bf16 v[76:79], v[158:161], v[198:201], v[76:79]
	v_mfma_f32_16x16x32_bf16 v[72:75], v[166:169], v[198:201], v[72:75]
	s_setprio 0
	s_barrier
	s_add_i32 s44, s23, s9
	s_add_u32 s98, s68, s52
	s_addc_u32 s99, s69, s53
	s_mov_b32 m0, s44
	ds_read_b128 v[202:205], v155
	ds_read_b128 v[206:209], v155 offset:1024
	ds_read_b128 v[210:213], v155 offset:2048
	ds_read_b128 v[214:217], v155 offset:3072
	global_load_lds_dwordx4 v130, s[68:69]
	s_add_i32 m0, s44, 0x2000
	s_nop 0
	global_load_lds_dwordx4 v134, s[68:69]
	s_barrier
	s_waitcnt lgkmcnt(0)
	s_setprio 1
	s_waitcnt lgkmcnt(0)
	v_mfma_f32_16x16x32_bf16 v[108:111], v[202:205], v[170:173], v[108:111]
	v_mfma_f32_16x16x32_bf16 v[104:107], v[210:213], v[170:173], v[104:107]
	v_mfma_f32_16x16x32_bf16 v[100:103], v[202:205], v[178:181], v[100:103]
	v_mfma_f32_16x16x32_bf16 v[96:99], v[210:213], v[178:181], v[96:99]
	v_mfma_f32_16x16x32_bf16 v[84:87], v[202:205], v[186:189], v[84:87]
	v_mfma_f32_16x16x32_bf16 v[80:83], v[210:213], v[186:189], v[80:83]
	v_mfma_f32_16x16x32_bf16 v[68:71], v[202:205], v[194:197], v[68:71]
	v_mfma_f32_16x16x32_bf16 v[64:67], v[210:213], v[194:197], v[64:67]
	v_mfma_f32_16x16x32_bf16 v[108:111], v[206:209], v[174:177], v[108:111]
	v_mfma_f32_16x16x32_bf16 v[104:107], v[214:217], v[174:177], v[104:107]
	v_mfma_f32_16x16x32_bf16 v[100:103], v[206:209], v[182:185], v[100:103]
	v_mfma_f32_16x16x32_bf16 v[96:99], v[214:217], v[182:185], v[96:99]
	v_mfma_f32_16x16x32_bf16 v[84:87], v[206:209], v[190:193], v[84:87]
	v_mfma_f32_16x16x32_bf16 v[80:83], v[214:217], v[190:193], v[80:83]
	v_mfma_f32_16x16x32_bf16 v[68:71], v[206:209], v[198:201], v[68:71]
	v_mfma_f32_16x16x32_bf16 v[64:67], v[214:217], v[198:201], v[64:67]
	s_setprio 0
	s_mov_b32 m0, s10
	s_add_u32 s100, s70, s52
	s_addc_u32 s101, s71, s53
	s_barrier
	ds_read_b128 v[170:173], v154 offset:16384
	ds_read_b128 v[174:177], v154 offset:17408
	ds_read_b128 v[178:181], v154 offset:18432
	ds_read_b128 v[182:185], v154 offset:19456
	ds_read_b128 v[186:189], v154 offset:20480
	ds_read_b128 v[190:193], v154 offset:21504
	ds_read_b128 v[194:197], v154 offset:22528
	ds_read_b128 v[198:201], v154 offset:23552
	global_load_lds_dwordx4 v128, s[70:71]
	s_mov_b32 m0, s11
	s_nop 0
	global_load_lds_dwordx4 v132, s[70:71]
	s_waitcnt vmcnt(10)
	s_barrier
	s_waitcnt lgkmcnt(0)
	s_setprio 1
	s_waitcnt lgkmcnt(0)
	v_mfma_f32_16x16x32_bf16 v[60:63], v[144:147], v[170:173], v[60:63]
	v_mfma_f32_16x16x32_bf16 v[56:59], v[162:165], v[170:173], v[56:59]
	v_mfma_f32_16x16x32_bf16 v[44:47], v[144:147], v[178:181], v[44:47]
	v_mfma_f32_16x16x32_bf16 v[40:43], v[162:165], v[178:181], v[40:43]
	v_mfma_f32_16x16x32_bf16 v[28:31], v[144:147], v[186:189], v[28:31]
	v_mfma_f32_16x16x32_bf16 v[24:27], v[162:165], v[186:189], v[24:27]
	v_mfma_f32_16x16x32_bf16 v[12:15], v[144:147], v[194:197], v[12:15]
	v_mfma_f32_16x16x32_bf16 v[8:11], v[162:165], v[194:197], v[8:11]
	v_mfma_f32_16x16x32_bf16 v[60:63], v[158:161], v[174:177], v[60:63]
	v_mfma_f32_16x16x32_bf16 v[56:59], v[166:169], v[174:177], v[56:59]
	v_mfma_f32_16x16x32_bf16 v[44:47], v[158:161], v[182:185], v[44:47]
	v_mfma_f32_16x16x32_bf16 v[40:43], v[166:169], v[182:185], v[40:43]
	v_mfma_f32_16x16x32_bf16 v[28:31], v[158:161], v[190:193], v[28:31]
	v_mfma_f32_16x16x32_bf16 v[24:27], v[166:169], v[190:193], v[24:27]
	v_mfma_f32_16x16x32_bf16 v[12:15], v[158:161], v[198:201], v[12:15]
	v_mfma_f32_16x16x32_bf16 v[8:11], v[166:169], v[198:201], v[8:11]
	s_setprio 0
	s_barrier
	s_add_u32 s44, s68, 0x80000
	s_addc_u32 s45, s69, 0
	s_add_i32 s46, s24, s9
	s_mov_b32 m0, s46
	s_nop 0
	global_load_lds_dwordx4 v130, s[44:45]
	s_add_i32 m0, s46, 0x2000
	s_nop 0
	global_load_lds_dwordx4 v134, s[44:45]
	s_add_i32 s46, 0, 0x18000
	v_add_u32_e32 v157, s46, v151
	ds_read_b128 v[144:147], v157
	ds_read_b128 v[158:161], v157 offset:1024
	ds_read_b128 v[162:165], v157 offset:2048
	ds_read_b128 v[166:169], v157 offset:3072
	s_waitcnt vmcnt(6)
	s_barrier
; #define PG8_STAGE(bufoff, gbase, voff) do { _Pragma("unroll") for (int _i = 0; _i < 2; ++_i) \
;         __builtin_amdgcn_global_load_lds((const unsigned*)((const char*)(gbase) + (voff)[_i]), (LAS unsigned*)(lds + (bufoff) + ldsw + _i * 8192), 16, 0, 0); } while (0)
; #define PG8_LDA(dst, b, h) do { _Pragma("unroll") for (int m = 0; m < 4; ++m) _Pragma("unroll") for (int k = 0; k < 2; ++k) dst[m][k] = *(const LAS bf16x8*)(lds + PG8_SA(b, h) + aoff + m * 2048 + k * 1024); } while (0)
; #define PG8_LDB(dst, b, h) do { _Pragma("unroll") for (int n = 0; n < 2; ++n) _Pragma("unroll") for (int k = 0; k < 2; ++k) dst[n][k] = *(const LAS bf16x8*)(lds + PG8_SB(b, h) + boff + n * 2048 + k * 1024); } while (0)
; #define PG8_MMA(ai, bj, At, Bt) do { __builtin_amdgcn_s_setprio(1); _Pragma("unroll") for (int m = 0; m < 4; ++m) _Pragma("unroll") for (int n = 0; n < 2; ++n) _Pragma("unroll") for (int k = 0; k < 2; ++k) \
;         acc[ai][bj][m][n] = __builtin_amdgcn_mfma_f32_16x16x32_bf16(Bt[n][k], At[m][k], acc[ai][bj][m][n], 0, 0, 0); __builtin_amdgcn_s_setprio(0); } while (0)
; #define PG8_WAIT_V(n) asm volatile("s_waitcnt vmcnt(" #n ")" ::: "memory")
; #define PG8_WAIT_L(n) asm volatile("s_waitcnt lgkmcnt(" #n ")" ::: "memory")
; #define PG8_BAR __builtin_amdgcn_s_barrier()
; #define PG8_SCHED __builtin_amdgcn_sched_barrier(0)
; template <class Epi>
; __device__ __forceinline__ void gemm_phase(LAS unsigned char* lds, const Gemm g, const StaticOrder& S, const Epi& E, int wv) {
;     ...
;             PG8_WAIT_V(6); PG8_BAR; PG8_MMA(1, 1, At, B1); PG8_BAR;
;             PG8_LDB(B0, 1, 0); PG8_SCHED; PG8_LDA(At, 1, 0); PG8_STAGE(PG8_SA(0, 1), a2 + hstepA, voffA);
;             PG8_WAIT_L(8); PG8_BAR; PG8_WAIT_L(0); PG8_MMA(0, 0, At, B0); PG8_BAR; PG8_SCHED;
;             PG8_LDB(B1, 1, 1); PG8_STAGE(PG8_SB(1, 0), b3, voffB);
;             PG8_BAR; PG8_WAIT_L(0); PG8_MMA(0, 1, At, B1); PG8_BAR;
;             PG8_LDA(At, 1, 1); PG8_STAGE(PG8_SA(1, 0), a3, voffA);
;             PG8_BAR; PG8_WAIT_L(0); PG8_MMA(1, 0, At, B0); PG8_BAR; PG8_SCHED;
	s_setprio 1
	v_mfma_f32_16x16x32_bf16 v[52:55], v[202:205], v[170:173], v[52:55]
	v_mfma_f32_16x16x32_bf16 v[48:51], v[210:213], v[170:173], v[48:51]
	v_mfma_f32_16x16x32_bf16 v[36:39], v[202:205], v[178:181], v[36:39]
	v_mfma_f32_16x16x32_bf16 v[32:35], v[210:213], v[178:181], v[32:35]
	v_mfma_f32_16x16x32_bf16 v[20:23], v[202:205], v[186:189], v[20:23]
	v_mfma_f32_16x16x32_bf16 v[16:19], v[210:213], v[186:189], v[16:19]
	v_mfma_f32_16x16x32_bf16 v[4:7], v[202:205], v[194:197], v[4:7]
	v_mfma_f32_16x16x32_bf16 v[0:3], v[210:213], v[194:197], v[0:3]
	v_mfma_f32_16x16x32_bf16 v[52:55], v[206:209], v[174:177], v[52:55]
	v_mfma_f32_16x16x32_bf16 v[48:51], v[214:217], v[174:177], v[48:51]
	v_mfma_f32_16x16x32_bf16 v[36:39], v[206:209], v[182:185], v[36:39]
	v_mfma_f32_16x16x32_bf16 v[32:35], v[214:217], v[182:185], v[32:35]
	v_mfma_f32_16x16x32_bf16 v[20:23], v[206:209], v[190:193], v[20:23]
	v_mfma_f32_16x16x32_bf16 v[16:19], v[214:217], v[190:193], v[16:19]
	v_mfma_f32_16x16x32_bf16 v[4:7], v[206:209], v[198:201], v[4:7]
	v_mfma_f32_16x16x32_bf16 v[0:3], v[214:217], v[198:201], v[0:3]
	s_setprio 0
	s_waitcnt lgkmcnt(0)
	s_barrier
	s_add_u32 s44, s70, 0x80000
	s_addc_u32 s45, s71, 0
	s_mov_b32 m0, s12
	ds_read_b128 v[170:173], v154 offset:32768
	ds_read_b128 v[174:177], v154 offset:33792
	ds_read_b128 v[178:181], v154 offset:34816
	ds_read_b128 v[182:185], v154 offset:35840
	ds_read_b128 v[186:189], v154 offset:36864
	ds_read_b128 v[190:193], v154 offset:37888
	ds_read_b128 v[194:197], v154 offset:38912
	ds_read_b128 v[198:201], v154 offset:39936
	global_load_lds_dwordx4 v128, s[44:45]
	s_mov_b32 m0, s13
	s_nop 0
	global_load_lds_dwordx4 v132, s[44:45]
	s_waitcnt lgkmcnt(8)
	s_barrier
	s_waitcnt lgkmcnt(0)
	s_setprio 1
	s_waitcnt lgkmcnt(0)
	v_mfma_f32_16x16x32_bf16 v[124:127], v[144:147], v[170:173], v[124:127]
	v_mfma_f32_16x16x32_bf16 v[120:123], v[162:165], v[170:173], v[120:123]
	v_mfma_f32_16x16x32_bf16 v[116:119], v[144:147], v[178:181], v[116:119]
	v_mfma_f32_16x16x32_bf16 v[112:115], v[162:165], v[178:181], v[112:115]
	v_mfma_f32_16x16x32_bf16 v[92:95], v[144:147], v[186:189], v[92:95]
	v_mfma_f32_16x16x32_bf16 v[88:91], v[162:165], v[186:189], v[88:91]
	v_mfma_f32_16x16x32_bf16 v[76:79], v[144:147], v[194:197], v[76:79]
	v_mfma_f32_16x16x32_bf16 v[72:75], v[162:165], v[194:197], v[72:75]
	v_mfma_f32_16x16x32_bf16 v[124:127], v[158:161], v[174:177], v[124:127]
	v_mfma_f32_16x16x32_bf16 v[120:123], v[166:169], v[174:177], v[120:123]
	v_mfma_f32_16x16x32_bf16 v[116:119], v[158:161], v[182:185], v[116:119]
	v_mfma_f32_16x16x32_bf16 v[112:115], v[166:169], v[182:185], v[112:115]
	v_mfma_f32_16x16x32_bf16 v[92:95], v[158:161], v[190:193], v[92:95]
	v_mfma_f32_16x16x32_bf16 v[88:91], v[166:169], v[190:193], v[88:91]
	v_mfma_f32_16x16x32_bf16 v[76:79], v[158:161], v[198:201], v[76:79]
	v_mfma_f32_16x16x32_bf16 v[72:75], v[166:169], v[198:201], v[72:75]
	s_setprio 0
	s_barrier
	s_add_i32 s47, 0, 0x1c000
	s_add_i32 s44, s46, s9
	v_add_u32_e32 v157, s47, v151
	s_mov_b32 m0, s44
	ds_read_b128 v[202:205], v157
	ds_read_b128 v[206:209], v157 offset:1024
	ds_read_b128 v[210:213], v157 offset:2048
	ds_read_b128 v[214:217], v157 offset:3072
	global_load_lds_dwordx4 v130, s[98:99]
	s_add_i32 m0, s44, 0x2000
	s_nop 0
	global_load_lds_dwordx4 v134, s[98:99]
	s_barrier
	s_waitcnt lgkmcnt(0)
	s_setprio 1
	s_waitcnt lgkmcnt(0)
	v_mfma_f32_16x16x32_bf16 v[108:111], v[202:205], v[170:173], v[108:111]
	v_mfma_f32_16x16x32_bf16 v[104:107], v[210:213], v[170:173], v[104:107]
	v_mfma_f32_16x16x32_bf16 v[100:103], v[202:205], v[178:181], v[100:103]
	v_mfma_f32_16x16x32_bf16 v[96:99], v[210:213], v[178:181], v[96:99]
	v_mfma_f32_16x16x32_bf16 v[84:87], v[202:205], v[186:189], v[84:87]
	v_mfma_f32_16x16x32_bf16 v[80:83], v[210:213], v[186:189], v[80:83]
	v_mfma_f32_16x16x32_bf16 v[68:71], v[202:205], v[194:197], v[68:71]
	v_mfma_f32_16x16x32_bf16 v[64:67], v[210:213], v[194:197], v[64:67]
	v_mfma_f32_16x16x32_bf16 v[108:111], v[206:209], v[174:177], v[108:111]
	v_mfma_f32_16x16x32_bf16 v[104:107], v[214:217], v[174:177], v[104:107]
	v_mfma_f32_16x16x32_bf16 v[100:103], v[206:209], v[182:185], v[100:103]
	v_mfma_f32_16x16x32_bf16 v[96:99], v[214:217], v[182:185], v[96:99]
	v_mfma_f32_16x16x32_bf16 v[84:87], v[206:209], v[190:193], v[84:87]
	v_mfma_f32_16x16x32_bf16 v[80:83], v[214:217], v[190:193], v[80:83]
	v_mfma_f32_16x16x32_bf16 v[68:71], v[206:209], v[198:201], v[68:71]
	v_mfma_f32_16x16x32_bf16 v[64:67], v[214:217], v[198:201], v[64:67]
	s_setprio 0
	s_mov_b32 m0, s15
	s_barrier
	ds_read_b128 v[170:173], v154 offset:49152
	ds_read_b128 v[174:177], v154 offset:50176
	ds_read_b128 v[178:181], v154 offset:51200
	ds_read_b128 v[182:185], v154 offset:52224
	ds_read_b128 v[186:189], v154 offset:53248
	ds_read_b128 v[190:193], v154 offset:54272
	ds_read_b128 v[194:197], v154 offset:55296
	ds_read_b128 v[198:201], v154 offset:56320
	global_load_lds_dwordx4 v128, s[100:101]
	s_mov_b32 m0, s22
	s_nop 0
	global_load_lds_dwordx4 v132, s[100:101]
	s_waitcnt vmcnt(10)
	s_barrier
	s_waitcnt lgkmcnt(0)
	s_setprio 1
	s_waitcnt lgkmcnt(0)
	v_mfma_f32_16x16x32_bf16 v[60:63], v[144:147], v[170:173], v[60:63]
	v_mfma_f32_16x16x32_bf16 v[56:59], v[162:165], v[170:173], v[56:59]
	v_mfma_f32_16x16x32_bf16 v[44:47], v[144:147], v[178:181], v[44:47]
	v_mfma_f32_16x16x32_bf16 v[40:43], v[162:165], v[178:181], v[40:43]
	v_mfma_f32_16x16x32_bf16 v[28:31], v[144:147], v[186:189], v[28:31]
	v_mfma_f32_16x16x32_bf16 v[24:27], v[162:165], v[186:189], v[24:27]
	v_mfma_f32_16x16x32_bf16 v[12:15], v[144:147], v[194:197], v[12:15]
	v_mfma_f32_16x16x32_bf16 v[8:11], v[162:165], v[194:197], v[8:11]
	v_mfma_f32_16x16x32_bf16 v[60:63], v[158:161], v[174:177], v[60:63]
	v_mfma_f32_16x16x32_bf16 v[56:59], v[166:169], v[174:177], v[56:59]
	v_mfma_f32_16x16x32_bf16 v[44:47], v[158:161], v[182:185], v[44:47]
	v_mfma_f32_16x16x32_bf16 v[40:43], v[166:169], v[182:185], v[40:43]
	v_mfma_f32_16x16x32_bf16 v[28:31], v[158:161], v[190:193], v[28:31]
	v_mfma_f32_16x16x32_bf16 v[24:27], v[166:169], v[190:193], v[24:27]
	v_mfma_f32_16x16x32_bf16 v[12:15], v[158:161], v[198:201], v[12:15]
	v_mfma_f32_16x16x32_bf16 v[8:11], v[166:169], v[198:201], v[8:11]
	s_setprio 0
	s_barrier
; __device__ __forceinline__ float fast_sigmoid(float x) { return __builtin_amdgcn_rcpf(1.0f + __builtin_amdgcn_exp2f(-x * LOG2E)); }
; __device__ __forceinline__ float ss_fix(float raw) { return (float)__float_as_uint(raw) * (1.0f / 256.0f); }
; #define PG8_STAGE(bufoff, gbase, voff) do { _Pragma("unroll") for (int _i = 0; _i < 2; ++_i) \
;         __builtin_amdgcn_global_load_lds((const unsigned*)((const char*)(gbase) + (voff)[_i]), (LAS unsigned*)(lds + (bufoff) + ldsw + _i * 8192), 16, 0, 0); } while (0)
; template <class Epi>
; __device__ __forceinline__ void gemm_phase(LAS unsigned char* lds, const Gemm g, const StaticOrder& S, const Epi& E, int wv) {
;     ...
;             PG8_STAGE(PG8_SB(1, 1), b3 + hstepB, voffB);
;             PG8_WAIT_V(6); PG8_BAR; PG8_MMA(1, 1, At, B1); PG8_BAR;
;     __device__ __forceinline__ void operator()(const f32x4 (&acc)[2][2][4][2], const Unit& u, int wr, int wc, int fr, int fq) const {
;     ...
;         float rsv[8];
; #pragma unroll
;         for (int it = 0; it < 8; ++it) rsv[it] = (SM == 1) ? ss[row0 + (it >> 2) * HALF + (it & 3) * 16] : 1.0f;
; #pragma unroll
;         for (int ai = 0; ai < 2; ++ai)
; #pragma unroll
;             for (int m = 0; m < 4; ++m) { const int row = row0 + ai * HALF + m * 16; float rs = 1.0f; if (SM == 1) rs = __builtin_amdgcn_rsqf(ss_fix(rsv[ai * 4 + m]) * (1.0f / DM) + EPS);
;                 bf16_t* rowp = base + (size_t)row * ldc + col0;
; #pragma unroll
;                 for (int bj = 0; bj < 2; ++bj) { f32x4 v0 = acc[ai][bj][m][0], v1 = acc[ai][bj][m][1];
;                     if (SM == 1) { v0 *= rs; v1 *= rs; }
;                     if (SM == 2) { v0 *= cs[bj][0]; v1 *= cs[bj][1]; }
;                     if (ACT == 1) {
; #pragma unroll
;                         for (int j = 0; j < 4; ++j) { const float a = fmaxf(v0[j], 0.f), b = fmaxf(v1[j], 0.f); v0[j] = a * a; v1[j] = b * b; } }
;                     if (ACT == 2) { if (tsel == 0) {
; #pragma unroll
;                         for (int j = 0; j < 4; ++j) { const float a = v0[j], b = v1[j];
;                             v0[j] = a * fast_sigmoid(1.5957691216057308f * (a + 0.044715f * a * a * a)); v1[j] = b * fast_sigmoid(1.5957691216057308f * (b + 0.044715f * b * b * b)); } } }
;                     u32x4 w; w.x = pk_bf16(v0[0], v0[1]); w.y = pk_bf16(v0[2], v0[3]); w.z = pk_bf16(v1[0], v1[1]); w.w = pk_bf16(v1[2], v1[3]);
	s_add_u32 s44, s68, 0x80080
	s_addc_u32 s45, s69, 0
	s_add_i32 s46, s47, s9
	s_mov_b32 m0, s46
	s_nop 0
	global_load_lds_dwordx4 v130, s[44:45]
	s_add_i32 m0, s46, 0x2000
	s_nop 0
	global_load_lds_dwordx4 v134, s[44:45]
	ds_read_b128 v[144:147], v153
	ds_read_b128 v[158:161], v153 offset:1024
	ds_read_b128 v[162:165], v153 offset:2048
	ds_read_b128 v[166:169], v153 offset:3072
	s_waitcnt vmcnt(6)
	s_barrier
	s_setprio 1
	v_mfma_f32_16x16x32_bf16 v[52:55], v[202:205], v[170:173], v[52:55]
	v_mfma_f32_16x16x32_bf16 v[48:51], v[210:213], v[170:173], v[48:51]
	v_mfma_f32_16x16x32_bf16 v[36:39], v[202:205], v[178:181], v[36:39]
	v_mfma_f32_16x16x32_bf16 v[32:35], v[210:213], v[178:181], v[32:35]
	v_mfma_f32_16x16x32_bf16 v[20:23], v[202:205], v[186:189], v[20:23]
	v_mfma_f32_16x16x32_bf16 v[16:19], v[210:213], v[186:189], v[16:19]
	v_mfma_f32_16x16x32_bf16 v[4:7], v[202:205], v[194:197], v[4:7]
	v_mfma_f32_16x16x32_bf16 v[0:3], v[210:213], v[194:197], v[0:3]
	v_mfma_f32_16x16x32_bf16 v[52:55], v[206:209], v[174:177], v[52:55]
	v_mfma_f32_16x16x32_bf16 v[48:51], v[214:217], v[174:177], v[48:51]
	v_mfma_f32_16x16x32_bf16 v[36:39], v[206:209], v[182:185], v[36:39]
	v_mfma_f32_16x16x32_bf16 v[32:35], v[214:217], v[182:185], v[32:35]
	v_mfma_f32_16x16x32_bf16 v[20:23], v[206:209], v[190:193], v[20:23]
	v_mfma_f32_16x16x32_bf16 v[16:19], v[214:217], v[190:193], v[16:19]
	v_mfma_f32_16x16x32_bf16 v[4:7], v[206:209], v[198:201], v[4:7]
	v_mfma_f32_16x16x32_bf16 v[0:3], v[214:217], v[198:201], v[0:3]
	s_setprio 0
	s_waitcnt lgkmcnt(0)
	s_add_i32 s43, s43, 2
	s_add_u32 s41, s41, 0x100
	s_addc_u32 s42, s42, 0
	s_add_u32 s66, s66, 0x100
	s_addc_u32 s67, s67, 0
	s_cmp_gt_u32 s43, 29
	s_barrier
	s_cbranch_scc0 .LBB0_530
	v_lshl_add_u32 v146, s64, 8, v150
	v_ashrrev_i32_e32 v147, 31, v146
	v_lshl_add_u64 v[144:145], v[146:147], 2, s[50:51]
	global_load_dword v157, v[144:145], off
	global_load_dword v162, v[144:145], off offset:64
	v_lshlrev_b64 v[160:161], 14, v[146:147]
	global_load_dword v166, v[144:145], off offset:128
	global_load_dword v167, v[144:145], off offset:192
	global_load_dword v168, v[144:145], off offset:512
	global_load_dword v169, v[144:145], off offset:576
	global_load_dword v170, v[144:145], off offset:640
	global_load_dword v147, v[144:145], off offset:704
	v_lshl_or_b32 v148, s34, 8, v152
	v_ashrrev_i32_e32 v149, 31, v148
	v_lshl_add_u64 v[148:149], v[148:149], 1, s[18:19]
	v_lshl_add_u64 v[144:145], v[148:149], 0, v[160:161]
	v_or_b32_e32 v158, 16, v146
	v_ashrrev_i32_e32 v159, 31, v158
	v_lshlrev_b64 v[158:159], 14, v[158:159]
	v_lshl_add_u64 v[158:159], v[148:149], 0, v[158:159]
	s_mov_b64 s[34:35], 0x200000
	s_mov_b32 s64, s58
	s_mov_b64 s[66:67], s[62:63]
	s_mov_b64 s[68:69], s[60:61]
	s_waitcnt vmcnt(0)
	v_cvt_f32_u32_e32 v157, v157
	v_cvt_f32_u32_e32 v161, v162
	v_mul_f32_e32 v157, 0x3b800000, v157
	v_fmamk_f32 v157, v157, 0x3a000000, v156
	v_rsq_f32_e32 v160, v157
	v_mul_f32_e32 v157, 0x3b800000, v161
	v_fmamk_f32 v157, v157, 0x3a000000, v156
	v_rsq_f32_e32 v162, v157
	v_pk_mul_f32 v[126:127], v[126:127], v[160:161] op_sel_hi:[1,0]
	v_pk_mul_f32 v[124:125], v[124:125], v[160:161] op_sel_hi:[1,0]
	v_pk_mul_f32 v[122:123], v[122:123], v[160:161] op_sel_hi:[1,0]
	v_pk_mul_f32 v[120:121], v[120:121], v[160:161] op_sel_hi:[1,0]
	v_pk_mul_f32 v[110:111], v[110:111], v[160:161] op_sel_hi:[1,0]
	v_pk_mul_f32 v[108:109], v[108:109], v[160:161] op_sel_hi:[1,0]
	v_pk_mul_f32 v[106:107], v[106:107], v[160:161] op_sel_hi:[1,0]
	v_pk_mul_f32 v[104:105], v[104:105], v[160:161] op_sel_hi:[1,0]
	v_pk_mul_f32 v[118:119], v[118:119], v[162:163] op_sel_hi:[1,0]
	v_pk_mul_f32 v[116:117], v[116:117], v[162:163] op_sel_hi:[1,0]
	v_pk_mul_f32 v[114:115], v[114:115], v[162:163] op_sel_hi:[1,0]
	v_pk_mul_f32 v[112:113], v[112:113], v[162:163] op_sel_hi:[1,0]
	v_pk_mul_f32 v[160:161], v[102:103], v[162:163] op_sel_hi:[1,0]
	v_pk_mul_f32 v[100:101], v[100:101], v[162:163] op_sel_hi:[1,0]
	v_pk_mul_f32 v[164:165], v[98:99], v[162:163] op_sel_hi:[1,0]
	v_pk_mul_f32 v[162:163], v[96:97], v[162:163] op_sel_hi:[1,0]
	v_max_f32_e32 v96, 0, v124
	v_max_f32_e32 v98, 0, v120
	v_max_f32_e32 v97, 0, v125
	v_max_f32_e32 v99, 0, v121
	v_max_f32_e32 v102, 0, v126
	v_max_f32_e32 v120, 0, v122
	v_max_f32_e32 v103, 0, v127
	v_max_f32_e32 v121, 0, v123
	v_max_f32_e32 v108, 0, v108
	v_max_f32_e32 v109, 0, v109
	v_max_f32_e32 v110, 0, v110
	v_max_f32_e32 v111, 0, v111
	v_max_f32_e32 v104, 0, v104
	v_max_f32_e32 v105, 0, v105
	v_max_f32_e32 v106, 0, v106
	v_max_f32_e32 v107, 0, v107
	v_max_f32_e32 v116, 0, v116
	v_max_f32_e32 v112, 0, v112
	v_max_f32_e32 v117, 0, v117
	v_max_f32_e32 v113, 0, v113
	v_max_f32_e32 v118, 0, v118
	v_max_f32_e32 v114, 0, v114
	v_max_f32_e32 v119, 0, v119
	v_max_f32_e32 v115, 0, v115
	v_max_f32_e32 v122, 0, v100
	v_max_f32_e32 v123, 0, v101
	v_pk_mul_f32 v[96:97], v[96:97], v[96:97]
	v_pk_mul_f32 v[98:99], v[98:99], v[98:99]
	v_pk_mul_f32 v[100:101], v[102:103], v[102:103]
	v_pk_mul_f32 v[102:103], v[120:121], v[120:121]
	v_pk_mul_f32 v[108:109], v[108:109], v[108:109]
	v_pk_mul_f32 v[110:111], v[110:111], v[110:111]
	v_pk_mul_f32 v[104:105], v[104:105], v[104:105]
	v_pk_mul_f32 v[106:107], v[106:107], v[106:107]
	v_pk_mul_f32 v[116:117], v[116:117], v[116:117]
	v_pk_mul_f32 v[112:113], v[112:113], v[112:113]
	v_pk_mul_f32 v[118:119], v[118:119], v[118:119]
	v_pk_mul_f32 v[114:115], v[114:115], v[114:115]
	v_cvt_pk_bf16_f32 v96, v96, v97
	v_cvt_pk_bf16_f32 v97, v100, v101
	v_cvt_pk_bf16_f32 v98, v98, v99
	v_cvt_pk_bf16_f32 v99, v102, v103
	v_cvt_pk_bf16_f32 v100, v108, v109
	v_cvt_pk_bf16_f32 v101, v110, v111
	v_cvt_pk_bf16_f32 v102, v104, v105
; __device__ __forceinline__ float fast_sigmoid(float x) { return __builtin_amdgcn_rcpf(1.0f + __builtin_amdgcn_exp2f(-x * LOG2E)); }
; __device__ __forceinline__ float ss_fix(float raw) { return (float)__float_as_uint(raw) * (1.0f / 256.0f); }
;     __device__ __forceinline__ const CAS char* base() const { const CAS char* ka = (const CAS char*)__builtin_amdgcn_kernarg_segment_ptr(); asm volatile("" : "+s"(ka)); return ka; }
;     __device__ __forceinline__ void operator()(const f32x4 (&acc)[2][2][4][2], const Unit& u, int wr, int wc, int fr, int fq) const {
;     ...
;             for (int m = 0; m < 4; ++m) { const int row = row0 + ai * HALF + m * 16; float rs = 1.0f; if (SM == 1) rs = __builtin_amdgcn_rsqf(ss_fix(rsv[ai * 4 + m]) * (1.0f / DM) + EPS);
;                 bf16_t* rowp = base + (size_t)row * ldc + col0;
; #pragma unroll
;                 for (int bj = 0; bj < 2; ++bj) { f32x4 v0 = acc[ai][bj][m][0], v1 = acc[ai][bj][m][1];
;                     if (SM == 1) { v0 *= rs; v1 *= rs; }
;                     if (SM == 2) { v0 *= cs[bj][0]; v1 *= cs[bj][1]; }
;                     if (ACT == 1) {
; #pragma unroll
;                         for (int j = 0; j < 4; ++j) { const float a = fmaxf(v0[j], 0.f), b = fmaxf(v1[j], 0.f); v0[j] = a * a; v1[j] = b * b; } }
;                     if (ACT == 2) { if (tsel == 0) {
; #pragma unroll
;                         for (int j = 0; j < 4; ++j) { const float a = v0[j], b = v1[j];
;                             v0[j] = a * fast_sigmoid(1.5957691216057308f * (a + 0.044715f * a * a * a)); v1[j] = b * fast_sigmoid(1.5957691216057308f * (b + 0.044715f * b * b * b)); } } }
;                     u32x4 w; w.x = pk_bf16(v0[0], v0[1]); w.y = pk_bf16(v0[2], v0[3]); w.z = pk_bf16(v1[0], v1[1]); w.w = pk_bf16(v1[2], v1[3]);
;                     *(u32x4*)(rowp + bj * HALF) = w; } }
	v_cvt_pk_bf16_f32 v103, v106, v107
	v_cvt_pk_bf16_f32 v104, v116, v117
	v_cvt_pk_bf16_f32 v105, v118, v119
	v_cvt_pk_bf16_f32 v106, v112, v113
	v_cvt_pk_bf16_f32 v107, v114, v115
	global_store_dwordx4 v[144:145], v[96:99], off sc1
	global_store_dwordx4 v[144:145], v[100:103], off offset:256 sc1
	global_store_dwordx4 v[158:159], v[104:107], off sc1
	v_pk_mul_f32 v[96:97], v[122:123], v[122:123]
	v_max_f32_e32 v100, 0, v160
	v_max_f32_e32 v101, 0, v161
	v_pk_mul_f32 v[100:101], v[100:101], v[100:101]
	v_cvt_pk_bf16_f32 v96, v96, v97
	v_cvt_pk_bf16_f32 v97, v100, v101
	v_cvt_f32_u32_e32 v100, v166
	v_max_f32_e32 v124, 0, v162
	v_max_f32_e32 v125, 0, v163
	v_max_f32_e32 v102, 0, v164
	v_max_f32_e32 v103, 0, v165
	v_pk_mul_f32 v[98:99], v[124:125], v[124:125]
	v_pk_mul_f32 v[102:103], v[102:103], v[102:103]
	v_cvt_pk_bf16_f32 v98, v98, v99
	v_cvt_pk_bf16_f32 v99, v102, v103
	global_store_dwordx4 v[158:159], v[96:99], off offset:256 sc1
	s_nop 1
	v_mul_f32_e32 v97, 0x3b800000, v100
	v_fmamk_f32 v97, v97, 0x3a000000, v156
	v_rsq_f32_e32 v98, v97
	v_or_b32_e32 v96, 32, v146
	v_ashrrev_i32_e32 v97, 31, v96
	v_lshlrev_b64 v[96:97], 14, v[96:97]
	v_pk_mul_f32 v[88:89], v[88:89], v[98:99] op_sel_hi:[1,0]
	v_pk_mul_f32 v[94:95], v[94:95], v[98:99] op_sel_hi:[1,0]
	v_pk_mul_f32 v[92:93], v[92:93], v[98:99] op_sel_hi:[1,0]
	v_pk_mul_f32 v[90:91], v[90:91], v[98:99] op_sel_hi:[1,0]
	v_max_f32_e32 v88, 0, v88
	v_max_f32_e32 v89, 0, v89
	v_max_f32_e32 v92, 0, v92
	v_max_f32_e32 v93, 0, v93
	v_pk_mul_f32 v[100:101], v[88:89], v[88:89]
	v_max_f32_e32 v88, 0, v94
	v_max_f32_e32 v90, 0, v90
	v_max_f32_e32 v89, 0, v95
	v_max_f32_e32 v91, 0, v91
	v_pk_mul_f32 v[92:93], v[92:93], v[92:93]
	v_pk_mul_f32 v[94:95], v[88:89], v[88:89]
	v_pk_mul_f32 v[102:103], v[90:91], v[90:91]
	v_pk_mul_f32 v[84:85], v[84:85], v[98:99] op_sel_hi:[1,0]
	v_pk_mul_f32 v[80:81], v[80:81], v[98:99] op_sel_hi:[1,0]
	v_lshl_add_u64 v[96:97], v[148:149], 0, v[96:97]
	v_cvt_pk_bf16_f32 v88, v92, v93
	v_cvt_pk_bf16_f32 v89, v94, v95
	v_cvt_pk_bf16_f32 v90, v100, v101
	v_cvt_pk_bf16_f32 v91, v102, v103
	v_pk_mul_f32 v[86:87], v[86:87], v[98:99] op_sel_hi:[1,0]
	v_max_f32_e32 v84, 0, v84
	v_max_f32_e32 v80, 0, v80
	v_max_f32_e32 v85, 0, v85
	v_max_f32_e32 v81, 0, v81
	global_store_dwordx4 v[96:97], v[88:91], off sc1
	v_pk_mul_f32 v[84:85], v[84:85], v[84:85]
	v_pk_mul_f32 v[82:83], v[82:83], v[98:99] op_sel_hi:[1,0]
	v_pk_mul_f32 v[88:89], v[80:81], v[80:81]
	v_max_f32_e32 v80, 0, v86
	v_max_f32_e32 v81, 0, v87
	v_pk_mul_f32 v[86:87], v[80:81], v[80:81]
	v_cvt_pk_bf16_f32 v80, v84, v85
	v_cvt_f32_u32_e32 v84, v167
	v_max_f32_e32 v82, 0, v82
	v_max_f32_e32 v83, 0, v83
	v_pk_mul_f32 v[90:91], v[82:83], v[82:83]
	v_cvt_pk_bf16_f32 v81, v86, v87
	v_cvt_pk_bf16_f32 v82, v88, v89
	v_cvt_pk_bf16_f32 v83, v90, v91
	global_store_dwordx4 v[96:97], v[80:83], off offset:256 sc1
	s_nop 1
	v_mul_f32_e32 v81, 0x3b800000, v84
	v_fmamk_f32 v81, v81, 0x3a000000, v156
	v_rsq_f32_e32 v82, v81
	v_or_b32_e32 v80, 48, v146
	v_ashrrev_i32_e32 v81, 31, v80
	v_lshlrev_b64 v[80:81], 14, v[80:81]
	v_pk_mul_f32 v[72:73], v[72:73], v[82:83] op_sel_hi:[1,0]
	v_pk_mul_f32 v[78:79], v[78:79], v[82:83] op_sel_hi:[1,0]
	v_pk_mul_f32 v[76:77], v[76:77], v[82:83] op_sel_hi:[1,0]
	v_pk_mul_f32 v[74:75], v[74:75], v[82:83] op_sel_hi:[1,0]
	v_max_f32_e32 v72, 0, v72
	v_max_f32_e32 v73, 0, v73
	v_max_f32_e32 v76, 0, v76
	v_max_f32_e32 v77, 0, v77
	v_pk_mul_f32 v[84:85], v[72:73], v[72:73]
	v_max_f32_e32 v72, 0, v78
	v_max_f32_e32 v74, 0, v74
	v_max_f32_e32 v73, 0, v79
	v_max_f32_e32 v75, 0, v75
	v_pk_mul_f32 v[76:77], v[76:77], v[76:77]
	v_pk_mul_f32 v[78:79], v[72:73], v[72:73]
	v_pk_mul_f32 v[86:87], v[74:75], v[74:75]
	v_pk_mul_f32 v[66:67], v[66:67], v[82:83] op_sel_hi:[1,0]
	v_lshl_add_u64 v[80:81], v[148:149], 0, v[80:81]
	v_cvt_pk_bf16_f32 v72, v76, v77
	v_cvt_pk_bf16_f32 v73, v78, v79
	v_cvt_pk_bf16_f32 v74, v84, v85
	v_cvt_pk_bf16_f32 v75, v86, v87
	v_max_f32_e32 v66, 0, v66
	v_max_f32_e32 v67, 0, v67
	global_store_dwordx4 v[80:81], v[72:75], off sc1
	v_pk_mul_f32 v[68:69], v[68:69], v[82:83] op_sel_hi:[1,0]
	v_pk_mul_f32 v[64:65], v[64:65], v[82:83] op_sel_hi:[1,0]
	v_pk_mul_f32 v[74:75], v[66:67], v[66:67]
	v_cvt_f32_u32_e32 v67, v168
	v_pk_mul_f32 v[70:71], v[70:71], v[82:83] op_sel_hi:[1,0]
	v_max_f32_e32 v68, 0, v68
	v_max_f32_e32 v64, 0, v64
	v_max_f32_e32 v69, 0, v69
	v_max_f32_e32 v65, 0, v65
	v_mul_f32_e32 v67, 0x3b800000, v67
	v_pk_mul_f32 v[68:69], v[68:69], v[68:69]
	v_pk_mul_f32 v[72:73], v[64:65], v[64:65]
	v_max_f32_e32 v64, 0, v70
	v_max_f32_e32 v65, 0, v71
	v_fmamk_f32 v67, v67, 0x3a000000, v156
	v_pk_mul_f32 v[70:71], v[64:65], v[64:65]
	v_cvt_pk_bf16_f32 v64, v68, v69
	v_rsq_f32_e32 v68, v67
	v_cvt_pk_bf16_f32 v65, v70, v71
	v_cvt_pk_bf16_f32 v66, v72, v73
	v_cvt_pk_bf16_f32 v67, v74, v75
	v_pk_mul_f32 v[60:61], v[60:61], v[68:69] op_sel_hi:[1,0]
	v_pk_mul_f32 v[56:57], v[56:57], v[68:69] op_sel_hi:[1,0]
	v_pk_mul_f32 v[62:63], v[62:63], v[68:69] op_sel_hi:[1,0]
	v_pk_mul_f32 v[58:59], v[58:59], v[68:69] op_sel_hi:[1,0]
	v_max_f32_e32 v60, 0, v60
	v_max_f32_e32 v56, 0, v56
	v_max_f32_e32 v61, 0, v61
	v_max_f32_e32 v57, 0, v57
	global_store_dwordx4 v[80:81], v[64:67], off offset:256 sc1
	v_pk_mul_f32 v[60:61], v[60:61], v[60:61]
	v_max_f32_e32 v58, 0, v58
	v_lshl_add_u64 v[64:65], v[144:145], 0, s[34:35]
	v_pk_mul_f32 v[66:67], v[56:57], v[56:57]
	v_max_f32_e32 v56, 0, v62
	v_max_f32_e32 v57, 0, v63
	v_max_f32_e32 v59, 0, v59
	s_mov_b32 s34, 0x200000
	v_pk_mul_f32 v[62:63], v[56:57], v[56:57]
	v_pk_mul_f32 v[70:71], v[58:59], v[58:59]
	v_cvt_pk_bf16_f32 v56, v60, v61
	v_add_co_u32_e32 v60, vcc, s34, v144
; __device__ __forceinline__ float fast_sigmoid(float x) { return __builtin_amdgcn_rcpf(1.0f + __builtin_amdgcn_exp2f(-x * LOG2E)); }
; __device__ __forceinline__ float ss_fix(float raw) { return (float)__float_as_uint(raw) * (1.0f / 256.0f); }
;     __device__ __forceinline__ const CAS char* base() const { const CAS char* ka = (const CAS char*)__builtin_amdgcn_kernarg_segment_ptr(); asm volatile("" : "+s"(ka)); return ka; }
;     __device__ __forceinline__ void operator()(const f32x4 (&acc)[2][2][4][2], const Unit& u, int wr, int wc, int fr, int fq) const {
;     ...
;             for (int m = 0; m < 4; ++m) { const int row = row0 + ai * HALF + m * 16; float rs = 1.0f; if (SM == 1) rs = __builtin_amdgcn_rsqf(ss_fix(rsv[ai * 4 + m]) * (1.0f / DM) + EPS);
;                 bf16_t* rowp = base + (size_t)row * ldc + col0;
; #pragma unroll
;                 for (int bj = 0; bj < 2; ++bj) { f32x4 v0 = acc[ai][bj][m][0], v1 = acc[ai][bj][m][1];
;                     if (SM == 1) { v0 *= rs; v1 *= rs; }
;                     if (SM == 2) { v0 *= cs[bj][0]; v1 *= cs[bj][1]; }
;                     if (ACT == 1) {
; #pragma unroll
;                         for (int j = 0; j < 4; ++j) { const float a = fmaxf(v0[j], 0.f), b = fmaxf(v1[j], 0.f); v0[j] = a * a; v1[j] = b * b; } }
;                     if (ACT == 2) { if (tsel == 0) {
; #pragma unroll
;                         for (int j = 0; j < 4; ++j) { const float a = v0[j], b = v1[j];
;                             v0[j] = a * fast_sigmoid(1.5957691216057308f * (a + 0.044715f * a * a * a)); v1[j] = b * fast_sigmoid(1.5957691216057308f * (b + 0.044715f * b * b * b)); } } }
;                     u32x4 w; w.x = pk_bf16(v0[0], v0[1]); w.y = pk_bf16(v0[2], v0[3]); w.z = pk_bf16(v1[0], v1[1]); w.w = pk_bf16(v1[2], v1[3]);
;                     *(u32x4*)(rowp + bj * HALF) = w; } }
	v_pk_mul_f32 v[50:51], v[50:51], v[68:69] op_sel_hi:[1,0]
	v_cvt_pk_bf16_f32 v57, v62, v63
	v_cvt_pk_bf16_f32 v58, v66, v67
	v_cvt_pk_bf16_f32 v59, v70, v71
	v_addc_co_u32_e32 v61, vcc, 0, v145, vcc
	v_max_f32_e32 v50, 0, v50
	v_max_f32_e32 v51, 0, v51
	global_store_dwordx4 v[60:61], v[56:59], off sc1
	v_pk_mul_f32 v[52:53], v[52:53], v[68:69] op_sel_hi:[1,0]
	v_pk_mul_f32 v[48:49], v[48:49], v[68:69] op_sel_hi:[1,0]
	v_pk_mul_f32 v[58:59], v[50:51], v[50:51]
	v_cvt_f32_u32_e32 v51, v169
	v_pk_mul_f32 v[54:55], v[54:55], v[68:69] op_sel_hi:[1,0]
	v_max_f32_e32 v52, 0, v52
	v_max_f32_e32 v48, 0, v48
	v_max_f32_e32 v53, 0, v53
	v_max_f32_e32 v49, 0, v49
	v_mul_f32_e32 v51, 0x3b800000, v51
	v_pk_mul_f32 v[52:53], v[52:53], v[52:53]
	v_pk_mul_f32 v[56:57], v[48:49], v[48:49]
	v_max_f32_e32 v48, 0, v54
	v_max_f32_e32 v49, 0, v55
	v_fmamk_f32 v51, v51, 0x3a000000, v156
	v_pk_mul_f32 v[54:55], v[48:49], v[48:49]
	v_cvt_pk_bf16_f32 v48, v52, v53
	v_rsq_f32_e32 v52, v51
	v_cvt_pk_bf16_f32 v49, v54, v55
	v_cvt_pk_bf16_f32 v50, v56, v57
	v_cvt_pk_bf16_f32 v51, v58, v59
	v_pk_mul_f32 v[44:45], v[44:45], v[52:53] op_sel_hi:[1,0]
	v_pk_mul_f32 v[40:41], v[40:41], v[52:53] op_sel_hi:[1,0]
	s_mov_b64 s[34:35], 0x240000
	v_pk_mul_f32 v[46:47], v[46:47], v[52:53] op_sel_hi:[1,0]
	v_pk_mul_f32 v[42:43], v[42:43], v[52:53] op_sel_hi:[1,0]
	v_max_f32_e32 v44, 0, v44
	v_max_f32_e32 v40, 0, v40
	v_max_f32_e32 v45, 0, v45
	v_max_f32_e32 v41, 0, v41
	global_store_dwordx4 v[64:65], v[48:51], off offset:256 sc1
	v_pk_mul_f32 v[44:45], v[44:45], v[44:45]
	v_max_f32_e32 v42, 0, v42
	v_lshl_add_u64 v[48:49], v[144:145], 0, s[34:35]
	v_pk_mul_f32 v[50:51], v[40:41], v[40:41]
	v_max_f32_e32 v40, 0, v46
	v_max_f32_e32 v41, 0, v47
	v_max_f32_e32 v43, 0, v43
	s_mov_b32 s34, 0x240000
	v_pk_mul_f32 v[46:47], v[40:41], v[40:41]
	v_pk_mul_f32 v[54:55], v[42:43], v[42:43]
	v_cvt_pk_bf16_f32 v40, v44, v45
	v_add_co_u32_e32 v44, vcc, s34, v144
	v_pk_mul_f32 v[34:35], v[34:35], v[52:53] op_sel_hi:[1,0]
	v_cvt_pk_bf16_f32 v41, v46, v47
	v_cvt_pk_bf16_f32 v42, v50, v51
	v_cvt_pk_bf16_f32 v43, v54, v55
	v_addc_co_u32_e32 v45, vcc, 0, v145, vcc
	v_max_f32_e32 v34, 0, v34
	v_max_f32_e32 v35, 0, v35
	global_store_dwordx4 v[44:45], v[40:43], off sc1
	v_pk_mul_f32 v[36:37], v[36:37], v[52:53] op_sel_hi:[1,0]
	v_pk_mul_f32 v[32:33], v[32:33], v[52:53] op_sel_hi:[1,0]
	v_pk_mul_f32 v[42:43], v[34:35], v[34:35]
	v_cvt_f32_u32_e32 v35, v170
	v_pk_mul_f32 v[38:39], v[38:39], v[52:53] op_sel_hi:[1,0]
	v_max_f32_e32 v36, 0, v36
	v_max_f32_e32 v32, 0, v32
	v_max_f32_e32 v37, 0, v37
	v_max_f32_e32 v33, 0, v33
	v_mul_f32_e32 v35, 0x3b800000, v35
	v_pk_mul_f32 v[36:37], v[36:37], v[36:37]
	v_pk_mul_f32 v[40:41], v[32:33], v[32:33]
	v_max_f32_e32 v32, 0, v38
	v_max_f32_e32 v33, 0, v39
	v_fmamk_f32 v35, v35, 0x3a000000, v156
	v_pk_mul_f32 v[38:39], v[32:33], v[32:33]
	v_cvt_pk_bf16_f32 v32, v36, v37
	v_rsq_f32_e32 v36, v35
	v_cvt_pk_bf16_f32 v33, v38, v39
	v_cvt_pk_bf16_f32 v34, v40, v41
	v_cvt_pk_bf16_f32 v35, v42, v43
	v_pk_mul_f32 v[28:29], v[28:29], v[36:37] op_sel_hi:[1,0]
	v_pk_mul_f32 v[24:25], v[24:25], v[36:37] op_sel_hi:[1,0]
	v_pk_mul_f32 v[30:31], v[30:31], v[36:37] op_sel_hi:[1,0]
	v_pk_mul_f32 v[26:27], v[26:27], v[36:37] op_sel_hi:[1,0]
	v_max_f32_e32 v28, 0, v28
	v_max_f32_e32 v24, 0, v24
	v_max_f32_e32 v29, 0, v29
	v_max_f32_e32 v25, 0, v25
	global_store_dwordx4 v[48:49], v[32:35], off offset:256 sc1
	v_pk_mul_f32 v[28:29], v[28:29], v[28:29]
	v_max_f32_e32 v26, 0, v26
	v_pk_mul_f32 v[34:35], v[24:25], v[24:25]
	v_max_f32_e32 v24, 0, v30
	v_max_f32_e32 v25, 0, v31
	v_max_f32_e32 v27, 0, v27
	v_pk_mul_f32 v[30:31], v[24:25], v[24:25]
	v_pk_mul_f32 v[38:39], v[26:27], v[26:27]
	v_cvt_pk_bf16_f32 v24, v28, v29
	v_add_co_u32_e32 v28, vcc, s25, v144
	v_pk_mul_f32 v[18:19], v[18:19], v[36:37] op_sel_hi:[1,0]
	v_cvt_pk_bf16_f32 v25, v30, v31
	v_cvt_pk_bf16_f32 v26, v34, v35
	v_cvt_pk_bf16_f32 v27, v38, v39
	v_addc_co_u32_e32 v29, vcc, 0, v145, vcc
	v_max_f32_e32 v18, 0, v18
	v_max_f32_e32 v19, 0, v19
	global_store_dwordx4 v[28:29], v[24:27], off sc1
	v_pk_mul_f32 v[20:21], v[20:21], v[36:37] op_sel_hi:[1,0]
	v_pk_mul_f32 v[16:17], v[16:17], v[36:37] op_sel_hi:[1,0]
	v_pk_mul_f32 v[26:27], v[18:19], v[18:19]
	v_cvt_f32_u32_e32 v19, v147
	v_pk_mul_f32 v[22:23], v[22:23], v[36:37] op_sel_hi:[1,0]
	v_max_f32_e32 v20, 0, v20
	v_max_f32_e32 v16, 0, v16
	v_max_f32_e32 v21, 0, v21
	v_max_f32_e32 v17, 0, v17
	v_mul_f32_e32 v19, 0x3b800000, v19
	v_pk_mul_f32 v[20:21], v[20:21], v[20:21]
	v_pk_mul_f32 v[24:25], v[16:17], v[16:17]
	v_max_f32_e32 v16, 0, v22
	v_max_f32_e32 v17, 0, v23
	v_fmamk_f32 v19, v19, 0x3a000000, v156
	v_pk_mul_f32 v[22:23], v[16:17], v[16:17]
	v_cvt_pk_bf16_f32 v16, v20, v21
	v_rsq_f32_e32 v20, v19
	s_mov_b64 s[34:35], 0x280000
	v_lshl_add_u64 v[32:33], v[144:145], 0, s[34:35]
	v_cvt_pk_bf16_f32 v17, v22, v23
	v_pk_mul_f32 v[12:13], v[12:13], v[20:21] op_sel_hi:[1,0]
	v_pk_mul_f32 v[8:9], v[8:9], v[20:21] op_sel_hi:[1,0]
	v_cvt_pk_bf16_f32 v18, v24, v25
	v_cvt_pk_bf16_f32 v19, v26, v27
	v_pk_mul_f32 v[14:15], v[14:15], v[20:21] op_sel_hi:[1,0]
	v_pk_mul_f32 v[10:11], v[10:11], v[20:21] op_sel_hi:[1,0]
	v_max_f32_e32 v12, 0, v12
	v_max_f32_e32 v8, 0, v8
	v_max_f32_e32 v13, 0, v13
	v_max_f32_e32 v9, 0, v9
	global_store_dwordx4 v[32:33], v[16:19], off offset:256 sc1
	v_pk_mul_f32 v[12:13], v[12:13], v[12:13]
	v_max_f32_e32 v10, 0, v10
	v_pk_mul_f32 v[18:19], v[8:9], v[8:9]
	v_max_f32_e32 v8, 0, v14
	v_max_f32_e32 v9, 0, v15
	v_max_f32_e32 v11, 0, v11
	v_pk_mul_f32 v[14:15], v[8:9], v[8:9]
	v_pk_mul_f32 v[22:23], v[10:11], v[10:11]
	v_cvt_pk_bf16_f32 v8, v12, v13
	v_add_co_u32_e32 v12, vcc, s33, v144
	v_pk_mul_f32 v[0:1], v[0:1], v[20:21] op_sel_hi:[1,0]
	v_cvt_pk_bf16_f32 v9, v14, v15
	v_cvt_pk_bf16_f32 v10, v18, v19
	v_cvt_pk_bf16_f32 v11, v22, v23
	v_addc_co_u32_e32 v13, vcc, 0, v145, vcc
	v_pk_mul_f32 v[6:7], v[6:7], v[20:21] op_sel_hi:[1,0]
	v_pk_mul_f32 v[4:5], v[4:5], v[20:21] op_sel_hi:[1,0]
	v_pk_mul_f32 v[2:3], v[2:3], v[20:21] op_sel_hi:[1,0]
	v_max_f32_e32 v0, 0, v0
	v_max_f32_e32 v1, 0, v1
	global_store_dwordx4 v[12:13], v[8:11], off sc1
	v_max_f32_e32 v4, 0, v4
	v_max_f32_e32 v5, 0, v5
	v_pk_mul_f32 v[8:9], v[0:1], v[0:1]
	v_max_f32_e32 v0, 0, v6
	v_max_f32_e32 v2, 0, v2
	v_max_f32_e32 v1, 0, v7
	v_max_f32_e32 v3, 0, v3
	v_pk_mul_f32 v[4:5], v[4:5], v[4:5]
	v_pk_mul_f32 v[6:7], v[0:1], v[0:1]
	v_pk_mul_f32 v[10:11], v[2:3], v[2:3]
	v_lshl_add_u64 v[16:17], v[144:145], 0, s[54:55]
	v_cvt_pk_bf16_f32 v0, v4, v5
	v_cvt_pk_bf16_f32 v1, v6, v7
	v_cvt_pk_bf16_f32 v2, v8, v9
	v_cvt_pk_bf16_f32 v3, v10, v11
	s_and_b64 vcc, exec, s[16:17]
	s_mov_b32 s34, s56
	global_store_dwordx4 v[16:17], v[0:3], off offset:256 sc1
	s_cbranch_vccz .LBB0_523
	s_waitcnt vmcnt(0)
	s_cmpk_gt_u32 s4, 0xff
	s_cbranch_scc1 .LBB0_534
	s_barrier

; #define PG8_STAGE(bufoff, gbase, voff) do { _Pragma("unroll") for (int _i = 0; _i < 2; ++_i) \
;         __builtin_amdgcn_global_load_lds((const unsigned*)((const char*)(gbase) + (voff)[_i]), (LAS unsigned*)(lds + (bufoff) + ldsw + _i * 8192), 16, 0, 0); } while (0)
; #define PG8_LDA(dst, b, h) do { _Pragma("unroll") for (int m = 0; m < 4; ++m) _Pragma("unroll") for (int k = 0; k < 2; ++k) dst[m][k] = *(const LAS bf16x8*)(lds + PG8_SA(b, h) + aoff + m * 2048 + k * 1024); } while (0)
; #define PG8_LDB(dst, b, h) do { _Pragma("unroll") for (int n = 0; n < 2; ++n) _Pragma("unroll") for (int k = 0; k < 2; ++k) dst[n][k] = *(const LAS bf16x8*)(lds + PG8_SB(b, h) + boff + n * 2048 + k * 1024); } while (0)
; #define PG8_MMA(ai, bj, At, Bt) do { __builtin_amdgcn_s_setprio(1); _Pragma("unroll") for (int m = 0; m < 4; ++m) _Pragma("unroll") for (int n = 0; n < 2; ++n) _Pragma("unroll") for (int k = 0; k < 2; ++k) \
;         acc[ai][bj][m][n] = __builtin_amdgcn_mfma_f32_16x16x32_bf16(Bt[n][k], At[m][k], acc[ai][bj][m][n], 0, 0, 0); __builtin_amdgcn_s_setprio(0); } while (0)
; #define PG8_WAIT_V(n) asm volatile("s_waitcnt vmcnt(" #n ")" ::: "memory")
; template <class Epi>
; __device__ __forceinline__ void gemm_phase(LAS unsigned char* lds, const Gemm g, const StaticOrder& S, const Epi& E, int wv) {
;     ...
;             const bool last = (t == nt - 2);
;             const char* a1 = cA + (ptrdiff_t)(t + 1) * kstep;
;             const char* a2 = last ? nA : cA + (ptrdiff_t)(t + 2) * kstep; const char* b2 = last ? nB : cB + (ptrdiff_t)(t + 2) * kstep;
;             const char* a3 = a2 + kstep; const char* b3 = b2 + kstep;
;             PG8_LDB(B0, 0, 0); PG8_SCHED; PG8_LDA(At, 0, 0); PG8_STAGE(PG8_SA(1, 1), a1 + hstepA, voffA);
;             PG8_WAIT_L(8); PG8_BAR; PG8_WAIT_L(0); PG8_MMA(0, 0, At, B0); PG8_BAR; PG8_SCHED;
;             PG8_LDB(B1, 0, 1); PG8_STAGE(PG8_SB(0, 0), b2, voffB);
;             PG8_BAR; PG8_WAIT_L(0); PG8_MMA(0, 1, At, B1); PG8_BAR;
;             PG8_LDA(At, 0, 1); PG8_STAGE(PG8_SA(0, 0), a2, voffA);
;             PG8_BAR; PG8_WAIT_L(0); PG8_MMA(1, 0, At, B0); PG8_BAR; PG8_SCHED;
;             PG8_STAGE(PG8_SB(0, 1), b2 + hstepB, voffB);
;             PG8_WAIT_V(6); PG8_BAR; PG8_MMA(1, 1, At, B1); PG8_BAR;
;             PG8_LDB(B0, 1, 0); PG8_SCHED; PG8_LDA(At, 1, 0); PG8_STAGE(PG8_SA(0, 1), a2 + hstepA, voffA);
.LBB0_1668:
	s_add_u32 s46, s44, 0xfff80080
	s_addc_u32 s47, s45, -1
	s_cmp_eq_u32 s66, 28
	s_cselect_b32 s49, s37, s47
	s_cselect_b32 s48, s62, s46
	s_cselect_b32 s47, s35, s65
	s_cselect_b32 s46, s63, s64
	s_add_i32 m0, s33, 0xc000
	ds_read_b128 v[170:173], v154
	ds_read_b128 v[174:177], v154 offset:1024
	ds_read_b128 v[178:181], v154 offset:2048
	ds_read_b128 v[182:185], v154 offset:3072
	ds_read_b128 v[186:189], v154 offset:4096
	ds_read_b128 v[190:193], v154 offset:5120
	ds_read_b128 v[194:197], v154 offset:6144
	ds_read_b128 v[198:201], v154 offset:7168
	global_load_lds_dwordx4 v138, s[44:45]
	s_add_i32 m0, s33, 0xe000
	s_nop 0
	global_load_lds_dwordx4 v136, s[44:45]
	s_waitcnt lgkmcnt(8)
	s_barrier
	s_waitcnt lgkmcnt(0)
	s_setprio 1
	s_waitcnt lgkmcnt(0)
	v_mfma_f32_16x16x32_bf16 v[124:127], v[144:147], v[170:173], v[124:127]
	v_mfma_f32_16x16x32_bf16 v[120:123], v[162:165], v[170:173], v[120:123]
	v_mfma_f32_16x16x32_bf16 v[116:119], v[144:147], v[178:181], v[116:119]
	v_mfma_f32_16x16x32_bf16 v[112:115], v[162:165], v[178:181], v[112:115]
	v_mfma_f32_16x16x32_bf16 v[92:95], v[144:147], v[186:189], v[92:95]
	v_mfma_f32_16x16x32_bf16 v[88:91], v[162:165], v[186:189], v[88:91]
	v_mfma_f32_16x16x32_bf16 v[76:79], v[144:147], v[194:197], v[76:79]
	v_mfma_f32_16x16x32_bf16 v[72:75], v[162:165], v[194:197], v[72:75]
	v_mfma_f32_16x16x32_bf16 v[124:127], v[158:161], v[174:177], v[124:127]
	v_mfma_f32_16x16x32_bf16 v[120:123], v[166:169], v[174:177], v[120:123]
	v_mfma_f32_16x16x32_bf16 v[116:119], v[158:161], v[182:185], v[116:119]
	v_mfma_f32_16x16x32_bf16 v[112:115], v[166:169], v[182:185], v[112:115]
	v_mfma_f32_16x16x32_bf16 v[92:95], v[158:161], v[190:193], v[92:95]
	v_mfma_f32_16x16x32_bf16 v[88:91], v[166:169], v[190:193], v[88:91]
	v_mfma_f32_16x16x32_bf16 v[76:79], v[158:161], v[198:201], v[76:79]
	v_mfma_f32_16x16x32_bf16 v[72:75], v[166:169], v[198:201], v[72:75]
	s_setprio 0
	s_barrier
	s_add_i32 s67, s55, s25
	s_add_u32 s98, s46, s12
	s_addc_u32 s99, s47, s13
	s_mov_b32 m0, s67
	ds_read_b128 v[202:205], v155
	ds_read_b128 v[206:209], v155 offset:1024
	ds_read_b128 v[210:213], v155 offset:2048
	ds_read_b128 v[214:217], v155 offset:3072
	global_load_lds_dwordx4 v130, s[46:47]
	s_add_i32 m0, s67, 0x2000
	s_nop 0
	global_load_lds_dwordx4 v134, s[46:47]
	s_barrier
	s_waitcnt lgkmcnt(0)
	s_setprio 1
	s_waitcnt lgkmcnt(0)
	v_mfma_f32_16x16x32_bf16 v[108:111], v[202:205], v[170:173], v[108:111]
	v_mfma_f32_16x16x32_bf16 v[104:107], v[210:213], v[170:173], v[104:107]
	v_mfma_f32_16x16x32_bf16 v[100:103], v[202:205], v[178:181], v[100:103]
	v_mfma_f32_16x16x32_bf16 v[96:99], v[210:213], v[178:181], v[96:99]
	v_mfma_f32_16x16x32_bf16 v[84:87], v[202:205], v[186:189], v[84:87]
	v_mfma_f32_16x16x32_bf16 v[80:83], v[210:213], v[186:189], v[80:83]
	v_mfma_f32_16x16x32_bf16 v[68:71], v[202:205], v[194:197], v[68:71]
	v_mfma_f32_16x16x32_bf16 v[64:67], v[210:213], v[194:197], v[64:67]
	v_mfma_f32_16x16x32_bf16 v[108:111], v[206:209], v[174:177], v[108:111]
	v_mfma_f32_16x16x32_bf16 v[104:107], v[214:217], v[174:177], v[104:107]
	v_mfma_f32_16x16x32_bf16 v[100:103], v[206:209], v[182:185], v[100:103]
	v_mfma_f32_16x16x32_bf16 v[96:99], v[214:217], v[182:185], v[96:99]
	v_mfma_f32_16x16x32_bf16 v[84:87], v[206:209], v[190:193], v[84:87]
	v_mfma_f32_16x16x32_bf16 v[80:83], v[214:217], v[190:193], v[80:83]
	v_mfma_f32_16x16x32_bf16 v[68:71], v[206:209], v[198:201], v[68:71]
	v_mfma_f32_16x16x32_bf16 v[64:67], v[214:217], v[198:201], v[64:67]
	s_setprio 0
	s_mov_b32 m0, s33
	s_add_u32 s100, s48, s12
	s_addc_u32 s101, s49, s13
	s_barrier
	ds_read_b128 v[170:173], v154 offset:16384
	ds_read_b128 v[174:177], v154 offset:17408
	ds_read_b128 v[178:181], v154 offset:18432
	ds_read_b128 v[182:185], v154 offset:19456
	ds_read_b128 v[186:189], v154 offset:20480
	ds_read_b128 v[190:193], v154 offset:21504
	ds_read_b128 v[194:197], v154 offset:22528
	ds_read_b128 v[198:201], v154 offset:23552
	global_load_lds_dwordx4 v128, s[48:49]
	s_mov_b32 m0, s43
	s_nop 0
	global_load_lds_dwordx4 v132, s[48:49]
	s_waitcnt vmcnt(10)
	s_barrier
	s_waitcnt lgkmcnt(0)
	s_setprio 1
	s_waitcnt lgkmcnt(0)
	v_mfma_f32_16x16x32_bf16 v[60:63], v[144:147], v[170:173], v[60:63]
	v_mfma_f32_16x16x32_bf16 v[56:59], v[162:165], v[170:173], v[56:59]
	v_mfma_f32_16x16x32_bf16 v[44:47], v[144:147], v[178:181], v[44:47]
	v_mfma_f32_16x16x32_bf16 v[40:43], v[162:165], v[178:181], v[40:43]
	v_mfma_f32_16x16x32_bf16 v[28:31], v[144:147], v[186:189], v[28:31]
	v_mfma_f32_16x16x32_bf16 v[24:27], v[162:165], v[186:189], v[24:27]
	v_mfma_f32_16x16x32_bf16 v[12:15], v[144:147], v[194:197], v[12:15]
	v_mfma_f32_16x16x32_bf16 v[8:11], v[162:165], v[194:197], v[8:11]
	v_mfma_f32_16x16x32_bf16 v[60:63], v[158:161], v[174:177], v[60:63]
	v_mfma_f32_16x16x32_bf16 v[56:59], v[166:169], v[174:177], v[56:59]
	v_mfma_f32_16x16x32_bf16 v[44:47], v[158:161], v[182:185], v[44:47]
	v_mfma_f32_16x16x32_bf16 v[40:43], v[166:169], v[182:185], v[40:43]
	v_mfma_f32_16x16x32_bf16 v[28:31], v[158:161], v[190:193], v[28:31]
	v_mfma_f32_16x16x32_bf16 v[24:27], v[166:169], v[190:193], v[24:27]
	v_mfma_f32_16x16x32_bf16 v[12:15], v[158:161], v[198:201], v[12:15]
	v_mfma_f32_16x16x32_bf16 v[8:11], v[166:169], v[198:201], v[8:11]
	s_setprio 0
	s_barrier
	s_add_u32 s68, s46, 0x80000
	s_addc_u32 s69, s47, 0
	s_add_i32 s67, s56, s25
	s_mov_b32 m0, s67
	s_nop 0
	global_load_lds_dwordx4 v130, s[68:69]
	s_add_i32 m0, s67, 0x2000
	s_nop 0
	global_load_lds_dwordx4 v134, s[68:69]
	s_add_i32 s67, 0, 0x18000
	v_add_u32_e32 v157, s67, v151
	ds_read_b128 v[144:147], v157
	ds_read_b128 v[158:161], v157 offset:1024
	ds_read_b128 v[162:165], v157 offset:2048
	ds_read_b128 v[166:169], v157 offset:3072
	s_waitcnt vmcnt(6)
	s_barrier
; #define PG8_STAGE(bufoff, gbase, voff) do { _Pragma("unroll") for (int _i = 0; _i < 2; ++_i) \
;         __builtin_amdgcn_global_load_lds((const unsigned*)((const char*)(gbase) + (voff)[_i]), (LAS unsigned*)(lds + (bufoff) + ldsw + _i * 8192), 16, 0, 0); } while (0)
; #define PG8_LDA(dst, b, h) do { _Pragma("unroll") for (int m = 0; m < 4; ++m) _Pragma("unroll") for (int k = 0; k < 2; ++k) dst[m][k] = *(const LAS bf16x8*)(lds + PG8_SA(b, h) + aoff + m * 2048 + k * 1024); } while (0)
; #define PG8_LDB(dst, b, h) do { _Pragma("unroll") for (int n = 0; n < 2; ++n) _Pragma("unroll") for (int k = 0; k < 2; ++k) dst[n][k] = *(const LAS bf16x8*)(lds + PG8_SB(b, h) + boff + n * 2048 + k * 1024); } while (0)
; #define PG8_MMA(ai, bj, At, Bt) do { __builtin_amdgcn_s_setprio(1); _Pragma("unroll") for (int m = 0; m < 4; ++m) _Pragma("unroll") for (int n = 0; n < 2; ++n) _Pragma("unroll") for (int k = 0; k < 2; ++k) \
;         acc[ai][bj][m][n] = __builtin_amdgcn_mfma_f32_16x16x32_bf16(Bt[n][k], At[m][k], acc[ai][bj][m][n], 0, 0, 0); __builtin_amdgcn_s_setprio(0); } while (0)
; #define PG8_WAIT_V(n) asm volatile("s_waitcnt vmcnt(" #n ")" ::: "memory")
; #define PG8_WAIT_L(n) asm volatile("s_waitcnt lgkmcnt(" #n ")" ::: "memory")
; #define PG8_BAR __builtin_amdgcn_s_barrier()
; #define PG8_SCHED __builtin_amdgcn_sched_barrier(0)
; template <class Epi>
; __device__ __forceinline__ void gemm_phase(LAS unsigned char* lds, const Gemm g, const StaticOrder& S, const Epi& E, int wv) {
;     ...
;             PG8_WAIT_V(6); PG8_BAR; PG8_MMA(1, 1, At, B1); PG8_BAR;
;             PG8_LDB(B0, 1, 0); PG8_SCHED; PG8_LDA(At, 1, 0); PG8_STAGE(PG8_SA(0, 1), a2 + hstepA, voffA);
;             PG8_WAIT_L(8); PG8_BAR; PG8_WAIT_L(0); PG8_MMA(0, 0, At, B0); PG8_BAR; PG8_SCHED;
;             PG8_LDB(B1, 1, 1); PG8_STAGE(PG8_SB(1, 0), b3, voffB);
;             PG8_BAR; PG8_WAIT_L(0); PG8_MMA(0, 1, At, B1); PG8_BAR;
;             PG8_LDA(At, 1, 1); PG8_STAGE(PG8_SA(1, 0), a3, voffA);
;             PG8_BAR; PG8_WAIT_L(0); PG8_MMA(1, 0, At, B0); PG8_BAR; PG8_SCHED;
	s_setprio 1
	v_mfma_f32_16x16x32_bf16 v[52:55], v[202:205], v[170:173], v[52:55]
	v_mfma_f32_16x16x32_bf16 v[48:51], v[210:213], v[170:173], v[48:51]
	v_mfma_f32_16x16x32_bf16 v[36:39], v[202:205], v[178:181], v[36:39]
	v_mfma_f32_16x16x32_bf16 v[32:35], v[210:213], v[178:181], v[32:35]
	v_mfma_f32_16x16x32_bf16 v[20:23], v[202:205], v[186:189], v[20:23]
	v_mfma_f32_16x16x32_bf16 v[16:19], v[210:213], v[186:189], v[16:19]
	v_mfma_f32_16x16x32_bf16 v[4:7], v[202:205], v[194:197], v[4:7]
	v_mfma_f32_16x16x32_bf16 v[0:3], v[210:213], v[194:197], v[0:3]
	v_mfma_f32_16x16x32_bf16 v[52:55], v[206:209], v[174:177], v[52:55]
	v_mfma_f32_16x16x32_bf16 v[48:51], v[214:217], v[174:177], v[48:51]
	v_mfma_f32_16x16x32_bf16 v[36:39], v[206:209], v[182:185], v[36:39]
	v_mfma_f32_16x16x32_bf16 v[32:35], v[214:217], v[182:185], v[32:35]
	v_mfma_f32_16x16x32_bf16 v[20:23], v[206:209], v[190:193], v[20:23]
	v_mfma_f32_16x16x32_bf16 v[16:19], v[214:217], v[190:193], v[16:19]
	v_mfma_f32_16x16x32_bf16 v[4:7], v[206:209], v[198:201], v[4:7]
	v_mfma_f32_16x16x32_bf16 v[0:3], v[214:217], v[198:201], v[0:3]
	s_setprio 0
	s_waitcnt lgkmcnt(0)
	s_barrier
	s_add_u32 s48, s48, 0x80000
	s_addc_u32 s49, s49, 0
	s_mov_b32 m0, s50
	ds_read_b128 v[170:173], v154 offset:32768
	ds_read_b128 v[174:177], v154 offset:33792
	ds_read_b128 v[178:181], v154 offset:34816
	ds_read_b128 v[182:185], v154 offset:35840
	ds_read_b128 v[186:189], v154 offset:36864
	ds_read_b128 v[190:193], v154 offset:37888
	ds_read_b128 v[194:197], v154 offset:38912
	ds_read_b128 v[198:201], v154 offset:39936
	global_load_lds_dwordx4 v128, s[48:49]
	s_mov_b32 m0, s51
	s_nop 0
	global_load_lds_dwordx4 v132, s[48:49]
	s_waitcnt lgkmcnt(8)
	s_barrier
	s_waitcnt lgkmcnt(0)
	s_setprio 1
	s_waitcnt lgkmcnt(0)
	v_mfma_f32_16x16x32_bf16 v[124:127], v[144:147], v[170:173], v[124:127]
	v_mfma_f32_16x16x32_bf16 v[120:123], v[162:165], v[170:173], v[120:123]
	v_mfma_f32_16x16x32_bf16 v[116:119], v[144:147], v[178:181], v[116:119]
	v_mfma_f32_16x16x32_bf16 v[112:115], v[162:165], v[178:181], v[112:115]
	v_mfma_f32_16x16x32_bf16 v[92:95], v[144:147], v[186:189], v[92:95]
	v_mfma_f32_16x16x32_bf16 v[88:91], v[162:165], v[186:189], v[88:91]
	v_mfma_f32_16x16x32_bf16 v[76:79], v[144:147], v[194:197], v[76:79]
	v_mfma_f32_16x16x32_bf16 v[72:75], v[162:165], v[194:197], v[72:75]
	v_mfma_f32_16x16x32_bf16 v[124:127], v[158:161], v[174:177], v[124:127]
	v_mfma_f32_16x16x32_bf16 v[120:123], v[166:169], v[174:177], v[120:123]
	v_mfma_f32_16x16x32_bf16 v[116:119], v[158:161], v[182:185], v[116:119]
	v_mfma_f32_16x16x32_bf16 v[112:115], v[166:169], v[182:185], v[112:115]
	v_mfma_f32_16x16x32_bf16 v[92:95], v[158:161], v[190:193], v[92:95]
	v_mfma_f32_16x16x32_bf16 v[88:91], v[166:169], v[190:193], v[88:91]
	v_mfma_f32_16x16x32_bf16 v[76:79], v[158:161], v[198:201], v[76:79]
	v_mfma_f32_16x16x32_bf16 v[72:75], v[166:169], v[198:201], v[72:75]
	s_setprio 0
	s_barrier
	s_add_i32 s48, 0, 0x1c000
	s_add_i32 s49, s67, s25
	v_add_u32_e32 v157, s48, v151
	s_mov_b32 m0, s49
	ds_read_b128 v[202:205], v157
	ds_read_b128 v[206:209], v157 offset:1024
	ds_read_b128 v[210:213], v157 offset:2048
	ds_read_b128 v[214:217], v157 offset:3072
	global_load_lds_dwordx4 v130, s[98:99]
	s_add_i32 m0, s49, 0x2000
	s_nop 0
	global_load_lds_dwordx4 v134, s[98:99]
	s_barrier
	s_waitcnt lgkmcnt(0)
	s_setprio 1
	s_waitcnt lgkmcnt(0)
	v_mfma_f32_16x16x32_bf16 v[108:111], v[202:205], v[170:173], v[108:111]
	v_mfma_f32_16x16x32_bf16 v[104:107], v[210:213], v[170:173], v[104:107]
	v_mfma_f32_16x16x32_bf16 v[100:103], v[202:205], v[178:181], v[100:103]
	v_mfma_f32_16x16x32_bf16 v[96:99], v[210:213], v[178:181], v[96:99]
	v_mfma_f32_16x16x32_bf16 v[84:87], v[202:205], v[186:189], v[84:87]
	v_mfma_f32_16x16x32_bf16 v[80:83], v[210:213], v[186:189], v[80:83]
	v_mfma_f32_16x16x32_bf16 v[68:71], v[202:205], v[194:197], v[68:71]
	v_mfma_f32_16x16x32_bf16 v[64:67], v[210:213], v[194:197], v[64:67]
	v_mfma_f32_16x16x32_bf16 v[108:111], v[206:209], v[174:177], v[108:111]
	v_mfma_f32_16x16x32_bf16 v[104:107], v[214:217], v[174:177], v[104:107]
	v_mfma_f32_16x16x32_bf16 v[100:103], v[206:209], v[182:185], v[100:103]
	v_mfma_f32_16x16x32_bf16 v[96:99], v[214:217], v[182:185], v[96:99]
	v_mfma_f32_16x16x32_bf16 v[84:87], v[206:209], v[190:193], v[84:87]
	v_mfma_f32_16x16x32_bf16 v[80:83], v[214:217], v[190:193], v[80:83]
	v_mfma_f32_16x16x32_bf16 v[68:71], v[206:209], v[198:201], v[68:71]
	v_mfma_f32_16x16x32_bf16 v[64:67], v[214:217], v[198:201], v[64:67]
	s_setprio 0
	s_mov_b32 m0, s53
	s_barrier
	ds_read_b128 v[170:173], v154 offset:49152
	ds_read_b128 v[174:177], v154 offset:50176
	ds_read_b128 v[178:181], v154 offset:51200
	ds_read_b128 v[182:185], v154 offset:52224
	ds_read_b128 v[186:189], v154 offset:53248
	ds_read_b128 v[190:193], v154 offset:54272
	ds_read_b128 v[194:197], v154 offset:55296
	ds_read_b128 v[198:201], v154 offset:56320
	global_load_lds_dwordx4 v128, s[100:101]
	s_mov_b32 m0, s54
	s_nop 0
	global_load_lds_dwordx4 v132, s[100:101]
	s_waitcnt vmcnt(10)
	s_barrier
	s_waitcnt lgkmcnt(0)
	s_setprio 1
	s_waitcnt lgkmcnt(0)
	v_mfma_f32_16x16x32_bf16 v[60:63], v[144:147], v[170:173], v[60:63]
	v_mfma_f32_16x16x32_bf16 v[56:59], v[162:165], v[170:173], v[56:59]
	v_mfma_f32_16x16x32_bf16 v[44:47], v[144:147], v[178:181], v[44:47]
	v_mfma_f32_16x16x32_bf16 v[40:43], v[162:165], v[178:181], v[40:43]
	v_mfma_f32_16x16x32_bf16 v[28:31], v[144:147], v[186:189], v[28:31]
	v_mfma_f32_16x16x32_bf16 v[24:27], v[162:165], v[186:189], v[24:27]
	v_mfma_f32_16x16x32_bf16 v[12:15], v[144:147], v[194:197], v[12:15]
	v_mfma_f32_16x16x32_bf16 v[8:11], v[162:165], v[194:197], v[8:11]
	v_mfma_f32_16x16x32_bf16 v[60:63], v[158:161], v[174:177], v[60:63]
	v_mfma_f32_16x16x32_bf16 v[56:59], v[166:169], v[174:177], v[56:59]
	v_mfma_f32_16x16x32_bf16 v[44:47], v[158:161], v[182:185], v[44:47]
	v_mfma_f32_16x16x32_bf16 v[40:43], v[166:169], v[182:185], v[40:43]
	v_mfma_f32_16x16x32_bf16 v[28:31], v[158:161], v[190:193], v[28:31]
	v_mfma_f32_16x16x32_bf16 v[24:27], v[166:169], v[190:193], v[24:27]
	v_mfma_f32_16x16x32_bf16 v[12:15], v[158:161], v[198:201], v[12:15]
	v_mfma_f32_16x16x32_bf16 v[8:11], v[166:169], v[198:201], v[8:11]
	s_setprio 0
	s_barrier
; __device__ __forceinline__ float fast_sigmoid(float x) { return __builtin_amdgcn_rcpf(1.0f + __builtin_amdgcn_exp2f(-x * LOG2E)); }
; __device__ __forceinline__ float ss_fix(float raw) { return (float)__float_as_uint(raw) * (1.0f / 256.0f); }
; #define PG8_STAGE(bufoff, gbase, voff) do { _Pragma("unroll") for (int _i = 0; _i < 2; ++_i) \
;         __builtin_amdgcn_global_load_lds((const unsigned*)((const char*)(gbase) + (voff)[_i]), (LAS unsigned*)(lds + (bufoff) + ldsw + _i * 8192), 16, 0, 0); } while (0)
; template <class Epi>
; __device__ __forceinline__ void gemm_phase(LAS unsigned char* lds, const Gemm g, const StaticOrder& S, const Epi& E, int wv) {
;     ...
;             PG8_STAGE(PG8_SB(1, 1), b3 + hstepB, voffB);
;             PG8_WAIT_V(6); PG8_BAR; PG8_MMA(1, 1, At, B1); PG8_BAR;
;     __device__ __forceinline__ void operator()(const f32x4 (&acc)[2][2][4][2], const Unit& u, int wr, int wc, int fr, int fq) const {
;     ...
;         float rsv[8];
; #pragma unroll
;         for (int it = 0; it < 8; ++it) rsv[it] = (SM == 1) ? ss[row0 + (it >> 2) * HALF + (it & 3) * 16] : 1.0f;
; #pragma unroll
;         for (int ai = 0; ai < 2; ++ai)
; #pragma unroll
;             for (int m = 0; m < 4; ++m) { const int row = row0 + ai * HALF + m * 16; float rs = 1.0f; if (SM == 1) rs = __builtin_amdgcn_rsqf(ss_fix(rsv[ai * 4 + m]) * (1.0f / DM) + EPS);
;                 bf16_t* rowp = base + (size_t)row * ldc + col0;
; #pragma unroll
;                 for (int bj = 0; bj < 2; ++bj) { f32x4 v0 = acc[ai][bj][m][0], v1 = acc[ai][bj][m][1];
;                     if (SM == 1) { v0 *= rs; v1 *= rs; }
;                     if (SM == 2) { v0 *= cs[bj][0]; v1 *= cs[bj][1]; }
;                     if (ACT == 1) {
; #pragma unroll
;                         for (int j = 0; j < 4; ++j) { const float a = fmaxf(v0[j], 0.f), b = fmaxf(v1[j], 0.f); v0[j] = a * a; v1[j] = b * b; } }
;                     if (ACT == 2) { if (tsel == 0) {
; #pragma unroll
;                         for (int j = 0; j < 4; ++j) { const float a = v0[j], b = v1[j];
;                             v0[j] = a * fast_sigmoid(1.5957691216057308f * (a + 0.044715f * a * a * a)); v1[j] = b * fast_sigmoid(1.5957691216057308f * (b + 0.044715f * b * b * b)); } } }
;                     u32x4 w; w.x = pk_bf16(v0[0], v0[1]); w.y = pk_bf16(v0[2], v0[3]); w.z = pk_bf16(v1[0], v1[1]); w.w = pk_bf16(v1[2], v1[3]);
	s_add_u32 s46, s46, 0x80080
	s_addc_u32 s47, s47, 0
	s_add_i32 s48, s48, s25
	s_mov_b32 m0, s48
	s_nop 0
	global_load_lds_dwordx4 v130, s[46:47]
	s_add_i32 m0, s48, 0x2000
	s_nop 0
	global_load_lds_dwordx4 v134, s[46:47]
	ds_read_b128 v[144:147], v153
	ds_read_b128 v[158:161], v153 offset:1024
	ds_read_b128 v[162:165], v153 offset:2048
	ds_read_b128 v[166:169], v153 offset:3072
	s_waitcnt vmcnt(6)
	s_barrier
	s_setprio 1
	v_mfma_f32_16x16x32_bf16 v[52:55], v[202:205], v[170:173], v[52:55]
	v_mfma_f32_16x16x32_bf16 v[48:51], v[210:213], v[170:173], v[48:51]
	v_mfma_f32_16x16x32_bf16 v[36:39], v[202:205], v[178:181], v[36:39]
	v_mfma_f32_16x16x32_bf16 v[32:35], v[210:213], v[178:181], v[32:35]
	v_mfma_f32_16x16x32_bf16 v[20:23], v[202:205], v[186:189], v[20:23]
	v_mfma_f32_16x16x32_bf16 v[16:19], v[210:213], v[186:189], v[16:19]
	v_mfma_f32_16x16x32_bf16 v[4:7], v[202:205], v[194:197], v[4:7]
	v_mfma_f32_16x16x32_bf16 v[0:3], v[210:213], v[194:197], v[0:3]
	v_mfma_f32_16x16x32_bf16 v[52:55], v[206:209], v[174:177], v[52:55]
	v_mfma_f32_16x16x32_bf16 v[48:51], v[214:217], v[174:177], v[48:51]
	v_mfma_f32_16x16x32_bf16 v[36:39], v[206:209], v[182:185], v[36:39]
	v_mfma_f32_16x16x32_bf16 v[32:35], v[214:217], v[182:185], v[32:35]
	v_mfma_f32_16x16x32_bf16 v[20:23], v[206:209], v[190:193], v[20:23]
	v_mfma_f32_16x16x32_bf16 v[16:19], v[214:217], v[190:193], v[16:19]
	v_mfma_f32_16x16x32_bf16 v[4:7], v[206:209], v[198:201], v[4:7]
	v_mfma_f32_16x16x32_bf16 v[0:3], v[214:217], v[198:201], v[0:3]
	s_setprio 0
	s_waitcnt lgkmcnt(0)
	s_add_i32 s66, s66, 2
	s_add_u32 s64, s64, 0x100
	s_addc_u32 s65, s65, 0
	s_add_u32 s44, s44, 0x100
	s_addc_u32 s45, s45, 0
	s_cmp_gt_u32 s66, 29
	s_barrier
	s_cbranch_scc0 .LBB0_1668
	v_lshl_add_u32 v146, s42, 8, v150
	v_ashrrev_i32_e32 v147, 31, v146
	v_lshl_add_u64 v[144:145], v[146:147], 2, s[10:11]
	global_load_dword v157, v[144:145], off
	global_load_dword v162, v[144:145], off offset:64
	v_lshlrev_b64 v[160:161], 14, v[146:147]
	global_load_dword v166, v[144:145], off offset:128
	global_load_dword v167, v[144:145], off offset:192
	global_load_dword v168, v[144:145], off offset:512
	global_load_dword v169, v[144:145], off offset:576
	global_load_dword v170, v[144:145], off offset:640
	global_load_dword v147, v[144:145], off offset:704
	v_lshl_or_b32 v148, s61, 8, v152
	v_ashrrev_i32_e32 v149, 31, v148
	v_lshl_add_u64 v[148:149], v[148:149], 1, s[8:9]
	v_lshl_add_u64 v[144:145], v[148:149], 0, v[160:161]
	v_or_b32_e32 v158, 16, v146
	v_ashrrev_i32_e32 v159, 31, v158
	v_lshlrev_b64 v[158:159], 14, v[158:159]
	v_lshl_add_u64 v[158:159], v[148:149], 0, v[158:159]
	s_mov_b32 s61, s34
	s_mov_b32 s42, s36
	s_mov_b64 s[44:45], s[40:41]
	s_mov_b64 s[46:47], s[38:39]
	s_waitcnt vmcnt(0)
	v_cvt_f32_u32_e32 v157, v157
	v_cvt_f32_u32_e32 v161, v162
	v_mul_f32_e32 v157, 0x3b800000, v157
	v_fmamk_f32 v157, v157, 0x3a000000, v156
	v_rsq_f32_e32 v160, v157
	v_mul_f32_e32 v157, 0x3b800000, v161
	v_fmamk_f32 v157, v157, 0x3a000000, v156
	v_rsq_f32_e32 v162, v157
	v_pk_mul_f32 v[126:127], v[126:127], v[160:161] op_sel_hi:[1,0]
	v_pk_mul_f32 v[124:125], v[124:125], v[160:161] op_sel_hi:[1,0]
	v_pk_mul_f32 v[122:123], v[122:123], v[160:161] op_sel_hi:[1,0]
	v_pk_mul_f32 v[120:121], v[120:121], v[160:161] op_sel_hi:[1,0]
	v_pk_mul_f32 v[110:111], v[110:111], v[160:161] op_sel_hi:[1,0]
	v_pk_mul_f32 v[108:109], v[108:109], v[160:161] op_sel_hi:[1,0]
	v_pk_mul_f32 v[106:107], v[106:107], v[160:161] op_sel_hi:[1,0]
	v_pk_mul_f32 v[104:105], v[104:105], v[160:161] op_sel_hi:[1,0]
	v_pk_mul_f32 v[118:119], v[118:119], v[162:163] op_sel_hi:[1,0]
	v_pk_mul_f32 v[116:117], v[116:117], v[162:163] op_sel_hi:[1,0]
	v_pk_mul_f32 v[114:115], v[114:115], v[162:163] op_sel_hi:[1,0]
	v_pk_mul_f32 v[112:113], v[112:113], v[162:163] op_sel_hi:[1,0]
	v_pk_mul_f32 v[160:161], v[102:103], v[162:163] op_sel_hi:[1,0]
	v_pk_mul_f32 v[100:101], v[100:101], v[162:163] op_sel_hi:[1,0]
	v_pk_mul_f32 v[164:165], v[98:99], v[162:163] op_sel_hi:[1,0]
	v_pk_mul_f32 v[162:163], v[96:97], v[162:163] op_sel_hi:[1,0]
	v_max_f32_e32 v96, 0, v124
	v_max_f32_e32 v98, 0, v120
	v_max_f32_e32 v97, 0, v125
	v_max_f32_e32 v99, 0, v121
	v_max_f32_e32 v102, 0, v126
	v_max_f32_e32 v120, 0, v122
	v_max_f32_e32 v103, 0, v127
	v_max_f32_e32 v121, 0, v123
	v_max_f32_e32 v108, 0, v108
	v_max_f32_e32 v109, 0, v109
	v_max_f32_e32 v110, 0, v110
	v_max_f32_e32 v111, 0, v111
	v_max_f32_e32 v104, 0, v104
	v_max_f32_e32 v105, 0, v105
	v_max_f32_e32 v106, 0, v106
	v_max_f32_e32 v107, 0, v107
	v_max_f32_e32 v116, 0, v116
	v_max_f32_e32 v112, 0, v112
	v_max_f32_e32 v117, 0, v117
	v_max_f32_e32 v113, 0, v113
	v_max_f32_e32 v118, 0, v118
	v_max_f32_e32 v114, 0, v114
	v_max_f32_e32 v119, 0, v119
	v_max_f32_e32 v115, 0, v115
	v_max_f32_e32 v122, 0, v100
	v_max_f32_e32 v123, 0, v101
	v_pk_mul_f32 v[96:97], v[96:97], v[96:97]
	v_pk_mul_f32 v[98:99], v[98:99], v[98:99]
	v_pk_mul_f32 v[100:101], v[102:103], v[102:103]
	v_pk_mul_f32 v[102:103], v[120:121], v[120:121]
	v_pk_mul_f32 v[108:109], v[108:109], v[108:109]
	v_pk_mul_f32 v[110:111], v[110:111], v[110:111]
	v_pk_mul_f32 v[104:105], v[104:105], v[104:105]
	v_pk_mul_f32 v[106:107], v[106:107], v[106:107]
	v_pk_mul_f32 v[116:117], v[116:117], v[116:117]
	v_pk_mul_f32 v[112:113], v[112:113], v[112:113]
	v_pk_mul_f32 v[118:119], v[118:119], v[118:119]
	v_pk_mul_f32 v[114:115], v[114:115], v[114:115]
	v_cvt_pk_bf16_f32 v96, v96, v97
	v_cvt_pk_bf16_f32 v97, v100, v101
	v_cvt_pk_bf16_f32 v98, v98, v99
	v_cvt_pk_bf16_f32 v99, v102, v103
	v_cvt_pk_bf16_f32 v100, v108, v109
	v_cvt_pk_bf16_f32 v101, v110, v111
	v_cvt_pk_bf16_f32 v102, v104, v105
; __device__ __forceinline__ float fast_sigmoid(float x) { return __builtin_amdgcn_rcpf(1.0f + __builtin_amdgcn_exp2f(-x * LOG2E)); }
; __device__ __forceinline__ float ss_fix(float raw) { return (float)__float_as_uint(raw) * (1.0f / 256.0f); }
;     __device__ __forceinline__ const CAS char* base() const { const CAS char* ka = (const CAS char*)__builtin_amdgcn_kernarg_segment_ptr(); asm volatile("" : "+s"(ka)); return ka; }
;     __device__ __forceinline__ void operator()(const f32x4 (&acc)[2][2][4][2], const Unit& u, int wr, int wc, int fr, int fq) const {
;     ...
;             for (int m = 0; m < 4; ++m) { const int row = row0 + ai * HALF + m * 16; float rs = 1.0f; if (SM == 1) rs = __builtin_amdgcn_rsqf(ss_fix(rsv[ai * 4 + m]) * (1.0f / DM) + EPS);
;                 bf16_t* rowp = base + (size_t)row * ldc + col0;
; #pragma unroll
;                 for (int bj = 0; bj < 2; ++bj) { f32x4 v0 = acc[ai][bj][m][0], v1 = acc[ai][bj][m][1];
;                     if (SM == 1) { v0 *= rs; v1 *= rs; }
;                     if (SM == 2) { v0 *= cs[bj][0]; v1 *= cs[bj][1]; }
;                     if (ACT == 1) {
; #pragma unroll
;                         for (int j = 0; j < 4; ++j) { const float a = fmaxf(v0[j], 0.f), b = fmaxf(v1[j], 0.f); v0[j] = a * a; v1[j] = b * b; } }
;                     if (ACT == 2) { if (tsel == 0) {
; #pragma unroll
;                         for (int j = 0; j < 4; ++j) { const float a = v0[j], b = v1[j];
;                             v0[j] = a * fast_sigmoid(1.5957691216057308f * (a + 0.044715f * a * a * a)); v1[j] = b * fast_sigmoid(1.5957691216057308f * (b + 0.044715f * b * b * b)); } } }
;                     u32x4 w; w.x = pk_bf16(v0[0], v0[1]); w.y = pk_bf16(v0[2], v0[3]); w.z = pk_bf16(v1[0], v1[1]); w.w = pk_bf16(v1[2], v1[3]);
;                     *(u32x4*)(rowp + bj * HALF) = w; } }
	v_cvt_pk_bf16_f32 v103, v106, v107
	v_cvt_pk_bf16_f32 v104, v116, v117
	v_cvt_pk_bf16_f32 v105, v118, v119
	v_cvt_pk_bf16_f32 v106, v112, v113
	v_cvt_pk_bf16_f32 v107, v114, v115
	global_store_dwordx4 v[144:145], v[96:99], off sc1
	global_store_dwordx4 v[144:145], v[100:103], off offset:256 sc1
	global_store_dwordx4 v[158:159], v[104:107], off sc1
	v_pk_mul_f32 v[96:97], v[122:123], v[122:123]
	v_max_f32_e32 v100, 0, v160
	v_max_f32_e32 v101, 0, v161
	v_pk_mul_f32 v[100:101], v[100:101], v[100:101]
	v_cvt_pk_bf16_f32 v96, v96, v97
	v_cvt_pk_bf16_f32 v97, v100, v101
	v_cvt_f32_u32_e32 v100, v166
	v_max_f32_e32 v124, 0, v162
	v_max_f32_e32 v125, 0, v163
	v_max_f32_e32 v102, 0, v164
	v_max_f32_e32 v103, 0, v165
	v_pk_mul_f32 v[98:99], v[124:125], v[124:125]
	v_pk_mul_f32 v[102:103], v[102:103], v[102:103]
	v_cvt_pk_bf16_f32 v98, v98, v99
	v_cvt_pk_bf16_f32 v99, v102, v103
	global_store_dwordx4 v[158:159], v[96:99], off offset:256 sc1
	s_nop 1
	v_mul_f32_e32 v97, 0x3b800000, v100
	v_fmamk_f32 v97, v97, 0x3a000000, v156
	v_rsq_f32_e32 v98, v97
	v_or_b32_e32 v96, 32, v146
	v_ashrrev_i32_e32 v97, 31, v96
	v_lshlrev_b64 v[96:97], 14, v[96:97]
	v_pk_mul_f32 v[88:89], v[88:89], v[98:99] op_sel_hi:[1,0]
	v_pk_mul_f32 v[94:95], v[94:95], v[98:99] op_sel_hi:[1,0]
	v_pk_mul_f32 v[92:93], v[92:93], v[98:99] op_sel_hi:[1,0]
	v_pk_mul_f32 v[90:91], v[90:91], v[98:99] op_sel_hi:[1,0]
	v_max_f32_e32 v88, 0, v88
	v_max_f32_e32 v89, 0, v89
	v_max_f32_e32 v92, 0, v92
	v_max_f32_e32 v93, 0, v93
	v_pk_mul_f32 v[100:101], v[88:89], v[88:89]
	v_max_f32_e32 v88, 0, v94
	v_max_f32_e32 v90, 0, v90
	v_max_f32_e32 v89, 0, v95
	v_max_f32_e32 v91, 0, v91
	v_pk_mul_f32 v[92:93], v[92:93], v[92:93]
	v_pk_mul_f32 v[94:95], v[88:89], v[88:89]
	v_pk_mul_f32 v[102:103], v[90:91], v[90:91]
	v_pk_mul_f32 v[84:85], v[84:85], v[98:99] op_sel_hi:[1,0]
	v_pk_mul_f32 v[80:81], v[80:81], v[98:99] op_sel_hi:[1,0]
	v_lshl_add_u64 v[96:97], v[148:149], 0, v[96:97]
	v_cvt_pk_bf16_f32 v88, v92, v93
	v_cvt_pk_bf16_f32 v89, v94, v95
	v_cvt_pk_bf16_f32 v90, v100, v101
	v_cvt_pk_bf16_f32 v91, v102, v103
	v_pk_mul_f32 v[86:87], v[86:87], v[98:99] op_sel_hi:[1,0]
	v_max_f32_e32 v84, 0, v84
	v_max_f32_e32 v80, 0, v80
	v_max_f32_e32 v85, 0, v85
	v_max_f32_e32 v81, 0, v81
	global_store_dwordx4 v[96:97], v[88:91], off sc1
	v_pk_mul_f32 v[84:85], v[84:85], v[84:85]
	v_pk_mul_f32 v[82:83], v[82:83], v[98:99] op_sel_hi:[1,0]
	v_pk_mul_f32 v[88:89], v[80:81], v[80:81]
	v_max_f32_e32 v80, 0, v86
	v_max_f32_e32 v81, 0, v87
	v_pk_mul_f32 v[86:87], v[80:81], v[80:81]
	v_cvt_pk_bf16_f32 v80, v84, v85
	v_cvt_f32_u32_e32 v84, v167
	v_max_f32_e32 v82, 0, v82
	v_max_f32_e32 v83, 0, v83
	v_pk_mul_f32 v[90:91], v[82:83], v[82:83]
	v_cvt_pk_bf16_f32 v81, v86, v87
	v_cvt_pk_bf16_f32 v82, v88, v89
	v_cvt_pk_bf16_f32 v83, v90, v91
	global_store_dwordx4 v[96:97], v[80:83], off offset:256 sc1
	s_nop 1
	v_mul_f32_e32 v81, 0x3b800000, v84
	v_fmamk_f32 v81, v81, 0x3a000000, v156
	v_rsq_f32_e32 v82, v81
	v_or_b32_e32 v80, 48, v146
	v_ashrrev_i32_e32 v81, 31, v80
	v_lshlrev_b64 v[80:81], 14, v[80:81]
	v_pk_mul_f32 v[72:73], v[72:73], v[82:83] op_sel_hi:[1,0]
	v_pk_mul_f32 v[78:79], v[78:79], v[82:83] op_sel_hi:[1,0]
	v_pk_mul_f32 v[76:77], v[76:77], v[82:83] op_sel_hi:[1,0]
	v_pk_mul_f32 v[74:75], v[74:75], v[82:83] op_sel_hi:[1,0]
	v_max_f32_e32 v72, 0, v72
	v_max_f32_e32 v73, 0, v73
	v_max_f32_e32 v76, 0, v76
	v_max_f32_e32 v77, 0, v77
	v_pk_mul_f32 v[84:85], v[72:73], v[72:73]
	v_max_f32_e32 v72, 0, v78
	v_max_f32_e32 v74, 0, v74
	v_max_f32_e32 v73, 0, v79
	v_max_f32_e32 v75, 0, v75
	v_pk_mul_f32 v[76:77], v[76:77], v[76:77]
	v_pk_mul_f32 v[78:79], v[72:73], v[72:73]
	v_pk_mul_f32 v[86:87], v[74:75], v[74:75]
	v_pk_mul_f32 v[66:67], v[66:67], v[82:83] op_sel_hi:[1,0]
	v_lshl_add_u64 v[80:81], v[148:149], 0, v[80:81]
	v_cvt_pk_bf16_f32 v72, v76, v77
	v_cvt_pk_bf16_f32 v73, v78, v79
	v_cvt_pk_bf16_f32 v74, v84, v85
	v_cvt_pk_bf16_f32 v75, v86, v87
	v_max_f32_e32 v66, 0, v66
	v_max_f32_e32 v67, 0, v67
	global_store_dwordx4 v[80:81], v[72:75], off sc1
	v_pk_mul_f32 v[68:69], v[68:69], v[82:83] op_sel_hi:[1,0]
	v_pk_mul_f32 v[64:65], v[64:65], v[82:83] op_sel_hi:[1,0]
	v_pk_mul_f32 v[74:75], v[66:67], v[66:67]
	v_cvt_f32_u32_e32 v67, v168
	v_pk_mul_f32 v[70:71], v[70:71], v[82:83] op_sel_hi:[1,0]
	v_max_f32_e32 v68, 0, v68
	v_max_f32_e32 v64, 0, v64
	v_max_f32_e32 v69, 0, v69
	v_max_f32_e32 v65, 0, v65
	v_mul_f32_e32 v67, 0x3b800000, v67
	v_pk_mul_f32 v[68:69], v[68:69], v[68:69]
	v_pk_mul_f32 v[72:73], v[64:65], v[64:65]
	v_max_f32_e32 v64, 0, v70
	v_max_f32_e32 v65, 0, v71
	v_fmamk_f32 v67, v67, 0x3a000000, v156
	v_pk_mul_f32 v[70:71], v[64:65], v[64:65]
	v_cvt_pk_bf16_f32 v64, v68, v69
	v_rsq_f32_e32 v68, v67
	v_cvt_pk_bf16_f32 v65, v70, v71
	v_cvt_pk_bf16_f32 v66, v72, v73
	v_cvt_pk_bf16_f32 v67, v74, v75
	v_pk_mul_f32 v[60:61], v[60:61], v[68:69] op_sel_hi:[1,0]
	v_pk_mul_f32 v[56:57], v[56:57], v[68:69] op_sel_hi:[1,0]
	v_pk_mul_f32 v[62:63], v[62:63], v[68:69] op_sel_hi:[1,0]
	v_pk_mul_f32 v[58:59], v[58:59], v[68:69] op_sel_hi:[1,0]
	v_max_f32_e32 v60, 0, v60
	v_max_f32_e32 v56, 0, v56
	v_max_f32_e32 v61, 0, v61
	v_max_f32_e32 v57, 0, v57
	global_store_dwordx4 v[80:81], v[64:67], off offset:256 sc1
	v_pk_mul_f32 v[60:61], v[60:61], v[60:61]
	v_max_f32_e32 v58, 0, v58
	v_pk_mul_f32 v[66:67], v[56:57], v[56:57]
	v_max_f32_e32 v56, 0, v62
	v_max_f32_e32 v57, 0, v63
	v_max_f32_e32 v59, 0, v59
	v_pk_mul_f32 v[62:63], v[56:57], v[56:57]
	v_pk_mul_f32 v[70:71], v[58:59], v[58:59]
	v_cvt_pk_bf16_f32 v56, v60, v61
	v_add_co_u32_e32 v60, vcc, s57, v144
	v_pk_mul_f32 v[50:51], v[50:51], v[68:69] op_sel_hi:[1,0]
; __device__ __forceinline__ float fast_sigmoid(float x) { return __builtin_amdgcn_rcpf(1.0f + __builtin_amdgcn_exp2f(-x * LOG2E)); }
; __device__ __forceinline__ float ss_fix(float raw) { return (float)__float_as_uint(raw) * (1.0f / 256.0f); }
;     __device__ __forceinline__ const CAS char* base() const { const CAS char* ka = (const CAS char*)__builtin_amdgcn_kernarg_segment_ptr(); asm volatile("" : "+s"(ka)); return ka; }
;     __device__ __forceinline__ void operator()(const f32x4 (&acc)[2][2][4][2], const Unit& u, int wr, int wc, int fr, int fq) const {
;     ...
;             for (int m = 0; m < 4; ++m) { const int row = row0 + ai * HALF + m * 16; float rs = 1.0f; if (SM == 1) rs = __builtin_amdgcn_rsqf(ss_fix(rsv[ai * 4 + m]) * (1.0f / DM) + EPS);
;                 bf16_t* rowp = base + (size_t)row * ldc + col0;
; #pragma unroll
;                 for (int bj = 0; bj < 2; ++bj) { f32x4 v0 = acc[ai][bj][m][0], v1 = acc[ai][bj][m][1];
;                     if (SM == 1) { v0 *= rs; v1 *= rs; }
;                     if (SM == 2) { v0 *= cs[bj][0]; v1 *= cs[bj][1]; }
;                     if (ACT == 1) {
; #pragma unroll
;                         for (int j = 0; j < 4; ++j) { const float a = fmaxf(v0[j], 0.f), b = fmaxf(v1[j], 0.f); v0[j] = a * a; v1[j] = b * b; } }
;                     if (ACT == 2) { if (tsel == 0) {
; #pragma unroll
;                         for (int j = 0; j < 4; ++j) { const float a = v0[j], b = v1[j];
;                             v0[j] = a * fast_sigmoid(1.5957691216057308f * (a + 0.044715f * a * a * a)); v1[j] = b * fast_sigmoid(1.5957691216057308f * (b + 0.044715f * b * b * b)); } } }
;                     u32x4 w; w.x = pk_bf16(v0[0], v0[1]); w.y = pk_bf16(v0[2], v0[3]); w.z = pk_bf16(v1[0], v1[1]); w.w = pk_bf16(v1[2], v1[3]);
;                     *(u32x4*)(rowp + bj * HALF) = w; } }
	v_cvt_pk_bf16_f32 v57, v62, v63
	v_cvt_pk_bf16_f32 v58, v66, v67
	v_cvt_pk_bf16_f32 v59, v70, v71
	v_addc_co_u32_e32 v61, vcc, 0, v145, vcc
	v_max_f32_e32 v50, 0, v50
	v_max_f32_e32 v51, 0, v51
	global_store_dwordx4 v[60:61], v[56:59], off sc1
	v_pk_mul_f32 v[52:53], v[52:53], v[68:69] op_sel_hi:[1,0]
	v_pk_mul_f32 v[48:49], v[48:49], v[68:69] op_sel_hi:[1,0]
	v_pk_mul_f32 v[58:59], v[50:51], v[50:51]
	v_cvt_f32_u32_e32 v51, v169
	v_pk_mul_f32 v[54:55], v[54:55], v[68:69] op_sel_hi:[1,0]
	v_max_f32_e32 v52, 0, v52
	v_max_f32_e32 v48, 0, v48
	v_max_f32_e32 v53, 0, v53
	v_max_f32_e32 v49, 0, v49
	v_mul_f32_e32 v51, 0x3b800000, v51
	v_pk_mul_f32 v[52:53], v[52:53], v[52:53]
	v_pk_mul_f32 v[56:57], v[48:49], v[48:49]
	v_max_f32_e32 v48, 0, v54
	v_max_f32_e32 v49, 0, v55
	v_fmamk_f32 v51, v51, 0x3a000000, v156
	v_pk_mul_f32 v[54:55], v[48:49], v[48:49]
	v_cvt_pk_bf16_f32 v48, v52, v53
	v_rsq_f32_e32 v52, v51
	v_lshl_add_u64 v[64:65], v[144:145], 0, s[14:15]
	v_cvt_pk_bf16_f32 v49, v54, v55
	v_cvt_pk_bf16_f32 v50, v56, v57
	v_pk_mul_f32 v[44:45], v[44:45], v[52:53] op_sel_hi:[1,0]
	v_pk_mul_f32 v[40:41], v[40:41], v[52:53] op_sel_hi:[1,0]
	v_cvt_pk_bf16_f32 v51, v58, v59
	v_pk_mul_f32 v[46:47], v[46:47], v[52:53] op_sel_hi:[1,0]
	v_pk_mul_f32 v[42:43], v[42:43], v[52:53] op_sel_hi:[1,0]
	v_max_f32_e32 v44, 0, v44
	v_max_f32_e32 v40, 0, v40
	v_max_f32_e32 v45, 0, v45
	v_max_f32_e32 v41, 0, v41
	global_store_dwordx4 v[64:65], v[48:51], off offset:256 sc1
	v_pk_mul_f32 v[44:45], v[44:45], v[44:45]
	v_max_f32_e32 v42, 0, v42
	v_pk_mul_f32 v[50:51], v[40:41], v[40:41]
	v_max_f32_e32 v40, 0, v46
	v_max_f32_e32 v41, 0, v47
	v_max_f32_e32 v43, 0, v43
	v_pk_mul_f32 v[46:47], v[40:41], v[40:41]
	v_pk_mul_f32 v[54:55], v[42:43], v[42:43]
	v_cvt_pk_bf16_f32 v40, v44, v45
	v_add_co_u32_e32 v44, vcc, s58, v144
	v_pk_mul_f32 v[34:35], v[34:35], v[52:53] op_sel_hi:[1,0]
	v_cvt_pk_bf16_f32 v41, v46, v47
	v_cvt_pk_bf16_f32 v42, v50, v51
	v_cvt_pk_bf16_f32 v43, v54, v55
	v_addc_co_u32_e32 v45, vcc, 0, v145, vcc
	v_max_f32_e32 v34, 0, v34
	v_max_f32_e32 v35, 0, v35
	global_store_dwordx4 v[44:45], v[40:43], off sc1
	v_pk_mul_f32 v[36:37], v[36:37], v[52:53] op_sel_hi:[1,0]
	v_pk_mul_f32 v[32:33], v[32:33], v[52:53] op_sel_hi:[1,0]
	v_pk_mul_f32 v[42:43], v[34:35], v[34:35]
	v_cvt_f32_u32_e32 v35, v170
	v_pk_mul_f32 v[38:39], v[38:39], v[52:53] op_sel_hi:[1,0]
	v_max_f32_e32 v36, 0, v36
	v_max_f32_e32 v32, 0, v32
	v_max_f32_e32 v37, 0, v37
	v_max_f32_e32 v33, 0, v33
	v_mul_f32_e32 v35, 0x3b800000, v35
	v_pk_mul_f32 v[36:37], v[36:37], v[36:37]
	v_pk_mul_f32 v[40:41], v[32:33], v[32:33]
	v_max_f32_e32 v32, 0, v38
	v_max_f32_e32 v33, 0, v39
	v_fmamk_f32 v35, v35, 0x3a000000, v156
	v_pk_mul_f32 v[38:39], v[32:33], v[32:33]
	v_cvt_pk_bf16_f32 v32, v36, v37
	v_rsq_f32_e32 v36, v35
	v_lshl_add_u64 v[48:49], v[144:145], 0, s[16:17]
	v_cvt_pk_bf16_f32 v33, v38, v39
	v_cvt_pk_bf16_f32 v34, v40, v41
	v_pk_mul_f32 v[28:29], v[28:29], v[36:37] op_sel_hi:[1,0]
	v_pk_mul_f32 v[24:25], v[24:25], v[36:37] op_sel_hi:[1,0]
	v_cvt_pk_bf16_f32 v35, v42, v43
	v_pk_mul_f32 v[30:31], v[30:31], v[36:37] op_sel_hi:[1,0]
	v_pk_mul_f32 v[26:27], v[26:27], v[36:37] op_sel_hi:[1,0]
	v_max_f32_e32 v28, 0, v28
	v_max_f32_e32 v24, 0, v24
	v_max_f32_e32 v29, 0, v29
	v_max_f32_e32 v25, 0, v25
	global_store_dwordx4 v[48:49], v[32:35], off offset:256 sc1
	v_pk_mul_f32 v[28:29], v[28:29], v[28:29]
	v_max_f32_e32 v26, 0, v26
	v_pk_mul_f32 v[34:35], v[24:25], v[24:25]
	v_max_f32_e32 v24, 0, v30
	v_max_f32_e32 v25, 0, v31
	v_max_f32_e32 v27, 0, v27
	v_pk_mul_f32 v[30:31], v[24:25], v[24:25]
	v_pk_mul_f32 v[38:39], v[26:27], v[26:27]
	v_cvt_pk_bf16_f32 v24, v28, v29
	v_add_co_u32_e32 v28, vcc, s59, v144
	v_pk_mul_f32 v[18:19], v[18:19], v[36:37] op_sel_hi:[1,0]
	v_cvt_pk_bf16_f32 v25, v30, v31
	v_cvt_pk_bf16_f32 v26, v34, v35
	v_cvt_pk_bf16_f32 v27, v38, v39
	v_addc_co_u32_e32 v29, vcc, 0, v145, vcc
	v_max_f32_e32 v18, 0, v18
	v_max_f32_e32 v19, 0, v19
	global_store_dwordx4 v[28:29], v[24:27], off sc1
	v_pk_mul_f32 v[20:21], v[20:21], v[36:37] op_sel_hi:[1,0]
	v_pk_mul_f32 v[16:17], v[16:17], v[36:37] op_sel_hi:[1,0]
	v_pk_mul_f32 v[26:27], v[18:19], v[18:19]
	v_cvt_f32_u32_e32 v19, v147
	v_pk_mul_f32 v[22:23], v[22:23], v[36:37] op_sel_hi:[1,0]
	v_max_f32_e32 v20, 0, v20
	v_max_f32_e32 v16, 0, v16
	v_max_f32_e32 v21, 0, v21
	v_max_f32_e32 v17, 0, v17
	v_mul_f32_e32 v19, 0x3b800000, v19
	v_pk_mul_f32 v[20:21], v[20:21], v[20:21]
	v_pk_mul_f32 v[24:25], v[16:17], v[16:17]
	v_max_f32_e32 v16, 0, v22
	v_max_f32_e32 v17, 0, v23
	v_fmamk_f32 v19, v19, 0x3a000000, v156
	v_pk_mul_f32 v[22:23], v[16:17], v[16:17]
	v_cvt_pk_bf16_f32 v16, v20, v21
	v_rsq_f32_e32 v20, v19
	v_lshl_add_u64 v[32:33], v[144:145], 0, s[18:19]
	v_cvt_pk_bf16_f32 v17, v22, v23
	v_cvt_pk_bf16_f32 v18, v24, v25
	v_pk_mul_f32 v[12:13], v[12:13], v[20:21] op_sel_hi:[1,0]
	v_pk_mul_f32 v[8:9], v[8:9], v[20:21] op_sel_hi:[1,0]
	v_cvt_pk_bf16_f32 v19, v26, v27
	v_pk_mul_f32 v[14:15], v[14:15], v[20:21] op_sel_hi:[1,0]
	v_pk_mul_f32 v[10:11], v[10:11], v[20:21] op_sel_hi:[1,0]
	v_max_f32_e32 v12, 0, v12
	v_max_f32_e32 v8, 0, v8
	v_max_f32_e32 v13, 0, v13
	v_max_f32_e32 v9, 0, v9
	global_store_dwordx4 v[32:33], v[16:19], off offset:256 sc1
	v_pk_mul_f32 v[12:13], v[12:13], v[12:13]
	v_max_f32_e32 v10, 0, v10
	v_pk_mul_f32 v[18:19], v[8:9], v[8:9]
	v_max_f32_e32 v8, 0, v14
	v_max_f32_e32 v9, 0, v15
	v_max_f32_e32 v11, 0, v11
	v_pk_mul_f32 v[14:15], v[8:9], v[8:9]
	v_pk_mul_f32 v[22:23], v[10:11], v[10:11]
	v_cvt_pk_bf16_f32 v8, v12, v13
	v_add_co_u32_e32 v12, vcc, s60, v144
	v_pk_mul_f32 v[0:1], v[0:1], v[20:21] op_sel_hi:[1,0]
	v_cvt_pk_bf16_f32 v9, v14, v15
	v_cvt_pk_bf16_f32 v10, v18, v19
	v_cvt_pk_bf16_f32 v11, v22, v23
	v_addc_co_u32_e32 v13, vcc, 0, v145, vcc
	v_pk_mul_f32 v[6:7], v[6:7], v[20:21] op_sel_hi:[1,0]
	v_pk_mul_f32 v[4:5], v[4:5], v[20:21] op_sel_hi:[1,0]
	v_pk_mul_f32 v[2:3], v[2:3], v[20:21] op_sel_hi:[1,0]
	v_max_f32_e32 v0, 0, v0
	v_max_f32_e32 v1, 0, v1
	global_store_dwordx4 v[12:13], v[8:11], off sc1
	v_max_f32_e32 v4, 0, v4
	v_max_f32_e32 v5, 0, v5
	v_pk_mul_f32 v[8:9], v[0:1], v[0:1]
	v_max_f32_e32 v0, 0, v6
	v_max_f32_e32 v2, 0, v2
	v_max_f32_e32 v1, 0, v7
	v_max_f32_e32 v3, 0, v3
	v_pk_mul_f32 v[4:5], v[4:5], v[4:5]
	v_pk_mul_f32 v[6:7], v[0:1], v[0:1]
	v_pk_mul_f32 v[10:11], v[2:3], v[2:3]
	v_lshl_add_u64 v[16:17], v[144:145], 0, s[30:31]
	v_cvt_pk_bf16_f32 v0, v4, v5
	v_cvt_pk_bf16_f32 v1, v6, v7
	v_cvt_pk_bf16_f32 v2, v8, v9
	v_cvt_pk_bf16_f32 v3, v10, v11
	s_and_b64 vcc, exec, s[6:7]
	global_store_dwordx4 v[16:17], v[0:3], off offset:256 sc1
	s_cbranch_vccz .LBB0_1661
	s_waitcnt vmcnt(0)
	s_cmpk_gt_u32 s4, 0xff
	s_cbranch_scc1 .LBB0_1672
	s_barrier
